# nt_stores_w1
# speedup vs baseline: 1.0466x; 1.0066x over previous
.LBB0_850:
	ds_read_b128 v[144:147], v151
	ds_read_b128 v[156:159], v151 offset:1024
	ds_read_b128 v[160:163], v151 offset:2048
	ds_read_b128 v[164:167], v151 offset:3072
	s_add_u32 s36, s34, 0xfffc0080
	s_addc_u32 s37, s35, -1
	s_cmp_eq_u32 s66, 12
	s_cselect_b32 s39, s27, s37
	s_cselect_b32 s38, s62, s36
	s_cselect_b32 s37, s25, s65
	s_cselect_b32 s36, s63, s64
	v_lshl_add_u64 v[172:173], s[34:35], 0, v[136:137]
	s_add_i32 m0, s42, 0xc000
	ds_read_b128 v[168:171], v152
	ds_read_b128 v[176:179], v152 offset:1024
	ds_read_b128 v[180:183], v152 offset:2048
	ds_read_b128 v[184:187], v152 offset:3072
	ds_read_b128 v[188:191], v152 offset:4096
	ds_read_b128 v[192:195], v152 offset:5120
	ds_read_b128 v[196:199], v152 offset:6144
	ds_read_b128 v[200:203], v152 offset:7168
	global_load_lds_dwordx4 v[172:173], off
	v_lshl_add_u64 v[172:173], s[34:35], 0, v[138:139]
	s_add_i32 m0, s42, 0xe000
	s_nop 0
	global_load_lds_dwordx4 v[172:173], off
	s_waitcnt lgkmcnt(8)
	s_barrier
	s_waitcnt lgkmcnt(0)
	s_setprio 1
	s_waitcnt lgkmcnt(0)
	v_mfma_f32_16x16x32_bf16 v[124:127], v[144:147], v[168:171], v[124:127]
	v_mfma_f32_16x16x32_bf16 v[120:123], v[160:163], v[168:171], v[120:123]
	v_mfma_f32_16x16x32_bf16 v[116:119], v[144:147], v[180:183], v[116:119]
	v_mfma_f32_16x16x32_bf16 v[112:115], v[160:163], v[180:183], v[112:115]
	v_mfma_f32_16x16x32_bf16 v[92:95], v[144:147], v[188:191], v[92:95]
	v_mfma_f32_16x16x32_bf16 v[88:91], v[160:163], v[188:191], v[88:91]
	v_mfma_f32_16x16x32_bf16 v[76:79], v[144:147], v[196:199], v[76:79]
	v_mfma_f32_16x16x32_bf16 v[72:75], v[160:163], v[196:199], v[72:75]
	v_mfma_f32_16x16x32_bf16 v[124:127], v[156:159], v[176:179], v[124:127]
	v_mfma_f32_16x16x32_bf16 v[120:123], v[164:167], v[176:179], v[120:123]
	v_mfma_f32_16x16x32_bf16 v[116:119], v[156:159], v[184:187], v[116:119]
	v_mfma_f32_16x16x32_bf16 v[112:115], v[164:167], v[184:187], v[112:115]
	v_mfma_f32_16x16x32_bf16 v[92:95], v[156:159], v[192:195], v[92:95]
	v_mfma_f32_16x16x32_bf16 v[88:91], v[164:167], v[192:195], v[88:91]
	v_mfma_f32_16x16x32_bf16 v[76:79], v[156:159], v[200:203], v[76:79]
	v_mfma_f32_16x16x32_bf16 v[72:75], v[164:167], v[200:203], v[72:75]
	s_setprio 0
	s_barrier
	s_add_i32 s67, s55, s41
	v_lshl_add_u64 v[172:173], s[36:37], 0, v[130:131]
	s_mov_b32 m0, s67
	ds_read_b128 v[204:207], v153
	ds_read_b128 v[212:215], v153 offset:1024
	ds_read_b128 v[216:219], v153 offset:2048
	ds_read_b128 v[220:223], v153 offset:3072
	global_load_lds_dwordx4 v[172:173], off
	v_lshl_add_u64 v[208:209], s[36:37], 0, v[134:135]
	s_add_i32 m0, s67, 0x2000
	s_nop 0
	global_load_lds_dwordx4 v[208:209], off
	s_barrier
	s_waitcnt lgkmcnt(0)
	s_setprio 1
	s_waitcnt lgkmcnt(0)
	v_mfma_f32_16x16x32_bf16 v[108:111], v[204:207], v[168:171], v[108:111]
	v_mfma_f32_16x16x32_bf16 v[104:107], v[216:219], v[168:171], v[104:107]
	v_mfma_f32_16x16x32_bf16 v[100:103], v[204:207], v[180:183], v[100:103]
	v_mfma_f32_16x16x32_bf16 v[96:99], v[216:219], v[180:183], v[96:99]
	v_mfma_f32_16x16x32_bf16 v[84:87], v[204:207], v[188:191], v[84:87]
	v_mfma_f32_16x16x32_bf16 v[80:83], v[216:219], v[188:191], v[80:83]
	v_mfma_f32_16x16x32_bf16 v[68:71], v[204:207], v[196:199], v[68:71]
	v_mfma_f32_16x16x32_bf16 v[64:67], v[216:219], v[196:199], v[64:67]
	v_mfma_f32_16x16x32_bf16 v[108:111], v[212:215], v[176:179], v[108:111]
	v_mfma_f32_16x16x32_bf16 v[104:107], v[220:223], v[176:179], v[104:107]
	v_mfma_f32_16x16x32_bf16 v[100:103], v[212:215], v[184:187], v[100:103]
	v_mfma_f32_16x16x32_bf16 v[96:99], v[220:223], v[184:187], v[96:99]
	v_mfma_f32_16x16x32_bf16 v[84:87], v[212:215], v[192:195], v[84:87]
	v_mfma_f32_16x16x32_bf16 v[80:83], v[220:223], v[192:195], v[80:83]
	v_mfma_f32_16x16x32_bf16 v[68:71], v[212:215], v[200:203], v[68:71]
	v_mfma_f32_16x16x32_bf16 v[64:67], v[220:223], v[200:203], v[64:67]
	s_setprio 0
	s_mov_b32 m0, s42
	v_lshl_add_u64 v[224:225], s[38:39], 0, v[128:129]
	s_barrier
	ds_read_b128 v[168:171], v152 offset:16384
	ds_read_b128 v[176:179], v152 offset:17408
	ds_read_b128 v[180:183], v152 offset:18432
	ds_read_b128 v[184:187], v152 offset:19456
	ds_read_b128 v[188:191], v152 offset:20480
	ds_read_b128 v[192:195], v152 offset:21504
	ds_read_b128 v[196:199], v152 offset:22528
	ds_read_b128 v[200:203], v152 offset:23552
	global_load_lds_dwordx4 v[224:225], off
	v_lshl_add_u64 v[226:227], s[38:39], 0, v[132:133]
	s_mov_b32 m0, s43
	s_nop 0
	global_load_lds_dwordx4 v[226:227], off
	s_barrier
	s_waitcnt lgkmcnt(0)
	s_setprio 1
	s_waitcnt lgkmcnt(0)
	v_mfma_f32_16x16x32_bf16 v[60:63], v[144:147], v[168:171], v[60:63]
	v_mfma_f32_16x16x32_bf16 v[56:59], v[160:163], v[168:171], v[56:59]
	v_mfma_f32_16x16x32_bf16 v[44:47], v[144:147], v[180:183], v[44:47]
	v_mfma_f32_16x16x32_bf16 v[40:43], v[160:163], v[180:183], v[40:43]
	v_mfma_f32_16x16x32_bf16 v[28:31], v[144:147], v[188:191], v[28:31]
	v_mfma_f32_16x16x32_bf16 v[24:27], v[160:163], v[188:191], v[24:27]
	v_mfma_f32_16x16x32_bf16 v[12:15], v[144:147], v[196:199], v[12:15]
	v_mfma_f32_16x16x32_bf16 v[8:11], v[160:163], v[196:199], v[8:11]
	v_mfma_f32_16x16x32_bf16 v[60:63], v[156:159], v[176:179], v[60:63]
	v_mfma_f32_16x16x32_bf16 v[56:59], v[164:167], v[176:179], v[56:59]
	v_mfma_f32_16x16x32_bf16 v[44:47], v[156:159], v[184:187], v[44:47]
	v_mfma_f32_16x16x32_bf16 v[40:43], v[164:167], v[184:187], v[40:43]
	v_mfma_f32_16x16x32_bf16 v[28:31], v[156:159], v[192:195], v[28:31]
	v_mfma_f32_16x16x32_bf16 v[24:27], v[164:167], v[192:195], v[24:27]
	v_mfma_f32_16x16x32_bf16 v[12:15], v[156:159], v[200:203], v[12:15]
	v_mfma_f32_16x16x32_bf16 v[8:11], v[164:167], v[200:203], v[8:11]
	s_setprio 0
	s_barrier
	s_add_u32 s68, s36, 0x40000
	s_addc_u32 s69, s37, 0
	s_add_i32 s67, s56, s41
	v_lshl_add_u64 v[144:145], s[68:69], 0, v[130:131]
	s_mov_b32 m0, s67
	s_nop 0
	global_load_lds_dwordx4 v[144:145], off
	v_lshl_add_u64 v[144:145], s[68:69], 0, v[134:135]
	s_add_i32 m0, s67, 0x2000
	s_nop 0
	global_load_lds_dwordx4 v[144:145], off
	s_waitcnt vmcnt(6)
	s_barrier
	s_setprio 1
	v_mfma_f32_16x16x32_bf16 v[52:55], v[204:207], v[168:171], v[52:55]
	v_mfma_f32_16x16x32_bf16 v[48:51], v[216:219], v[168:171], v[48:51]
	v_mfma_f32_16x16x32_bf16 v[36:39], v[204:207], v[180:183], v[36:39]
	v_mfma_f32_16x16x32_bf16 v[32:35], v[216:219], v[180:183], v[32:35]
	v_mfma_f32_16x16x32_bf16 v[20:23], v[204:207], v[188:191], v[20:23]
	v_mfma_f32_16x16x32_bf16 v[16:19], v[216:219], v[188:191], v[16:19]
	v_mfma_f32_16x16x32_bf16 v[4:7], v[204:207], v[196:199], v[4:7]
	v_mfma_f32_16x16x32_bf16 v[0:3], v[216:219], v[196:199], v[0:3]
	v_mfma_f32_16x16x32_bf16 v[52:55], v[212:215], v[176:179], v[52:55]
	v_mfma_f32_16x16x32_bf16 v[48:51], v[220:223], v[176:179], v[48:51]
	v_mfma_f32_16x16x32_bf16 v[36:39], v[212:215], v[184:187], v[36:39]
	v_mfma_f32_16x16x32_bf16 v[32:35], v[220:223], v[184:187], v[32:35]
	v_mfma_f32_16x16x32_bf16 v[20:23], v[212:215], v[192:195], v[20:23]
	v_mfma_f32_16x16x32_bf16 v[16:19], v[220:223], v[192:195], v[16:19]
	v_mfma_f32_16x16x32_bf16 v[4:7], v[212:215], v[200:203], v[4:7]
	v_mfma_f32_16x16x32_bf16 v[0:3], v[220:223], v[200:203], v[0:3]
	s_setprio 0
	s_add_i32 s67, 0, 0x18000
	v_add_u32_e32 v155, s67, v149
	s_barrier
	ds_read_b128 v[144:147], v155
	ds_read_b128 v[156:159], v155 offset:1024
	ds_read_b128 v[160:163], v155 offset:2048
	ds_read_b128 v[164:167], v155 offset:3072
	s_add_u32 s38, s38, 0x40000
	s_addc_u32 s39, s39, 0
	s_mov_b32 m0, s48
	v_lshl_add_u64 v[204:205], s[38:39], 0, v[128:129]
	ds_read_b128 v[168:171], v152 offset:32768
	ds_read_b128 v[176:179], v152 offset:33792
	ds_read_b128 v[180:183], v152 offset:34816
	ds_read_b128 v[184:187], v152 offset:35840
	ds_read_b128 v[188:191], v152 offset:36864
	ds_read_b128 v[192:195], v152 offset:37888
	ds_read_b128 v[196:199], v152 offset:38912
	ds_read_b128 v[200:203], v152 offset:39936
	global_load_lds_dwordx4 v[204:205], off
	v_lshl_add_u64 v[204:205], s[38:39], 0, v[132:133]
	s_mov_b32 m0, s49
	s_nop 0
	global_load_lds_dwordx4 v[204:205], off
	s_waitcnt lgkmcnt(8)
	s_barrier
	s_waitcnt lgkmcnt(0)
	s_setprio 1
	s_waitcnt lgkmcnt(0)
	v_mfma_f32_16x16x32_bf16 v[124:127], v[144:147], v[168:171], v[124:127]
	v_mfma_f32_16x16x32_bf16 v[120:123], v[160:163], v[168:171], v[120:123]
	v_mfma_f32_16x16x32_bf16 v[116:119], v[144:147], v[180:183], v[116:119]
	v_mfma_f32_16x16x32_bf16 v[112:115], v[160:163], v[180:183], v[112:115]
	v_mfma_f32_16x16x32_bf16 v[92:95], v[144:147], v[188:191], v[92:95]
	v_mfma_f32_16x16x32_bf16 v[88:91], v[160:163], v[188:191], v[88:91]
	v_mfma_f32_16x16x32_bf16 v[76:79], v[144:147], v[196:199], v[76:79]
	v_mfma_f32_16x16x32_bf16 v[72:75], v[160:163], v[196:199], v[72:75]
	v_mfma_f32_16x16x32_bf16 v[124:127], v[156:159], v[176:179], v[124:127]
	v_mfma_f32_16x16x32_bf16 v[120:123], v[164:167], v[176:179], v[120:123]
	v_mfma_f32_16x16x32_bf16 v[116:119], v[156:159], v[184:187], v[116:119]
	v_mfma_f32_16x16x32_bf16 v[112:115], v[164:167], v[184:187], v[112:115]
	v_mfma_f32_16x16x32_bf16 v[92:95], v[156:159], v[192:195], v[92:95]
	v_mfma_f32_16x16x32_bf16 v[88:91], v[164:167], v[192:195], v[88:91]
	v_mfma_f32_16x16x32_bf16 v[76:79], v[156:159], v[200:203], v[76:79]
	v_mfma_f32_16x16x32_bf16 v[72:75], v[164:167], v[200:203], v[72:75]
	s_setprio 0
	s_barrier
	s_add_i32 s38, 0, 0x1c000
	s_add_i32 s39, s67, s41
	v_add_u32_e32 v155, s38, v149
	v_lshl_add_u64 v[172:173], v[172:173], 0, s[8:9]
	s_mov_b32 m0, s39
	ds_read_b128 v[204:207], v155
	ds_read_b128 v[212:215], v155 offset:1024
	ds_read_b128 v[216:219], v155 offset:2048
	ds_read_b128 v[220:223], v155 offset:3072
	global_load_lds_dwordx4 v[172:173], off
	v_lshl_add_u64 v[172:173], v[208:209], 0, s[8:9]
	s_add_i32 m0, s39, 0x2000
	s_nop 0
	global_load_lds_dwordx4 v[172:173], off
	s_barrier
	s_waitcnt lgkmcnt(0)
	s_setprio 1
	s_waitcnt lgkmcnt(0)
	v_mfma_f32_16x16x32_bf16 v[108:111], v[204:207], v[168:171], v[108:111]
	v_mfma_f32_16x16x32_bf16 v[104:107], v[216:219], v[168:171], v[104:107]
	v_mfma_f32_16x16x32_bf16 v[100:103], v[204:207], v[180:183], v[100:103]
	v_mfma_f32_16x16x32_bf16 v[96:99], v[216:219], v[180:183], v[96:99]
	v_mfma_f32_16x16x32_bf16 v[84:87], v[204:207], v[188:191], v[84:87]
	v_mfma_f32_16x16x32_bf16 v[80:83], v[216:219], v[188:191], v[80:83]
	v_mfma_f32_16x16x32_bf16 v[68:71], v[204:207], v[196:199], v[68:71]
	v_mfma_f32_16x16x32_bf16 v[64:67], v[216:219], v[196:199], v[64:67]
	v_mfma_f32_16x16x32_bf16 v[108:111], v[212:215], v[176:179], v[108:111]
	v_mfma_f32_16x16x32_bf16 v[104:107], v[220:223], v[176:179], v[104:107]
	v_mfma_f32_16x16x32_bf16 v[100:103], v[212:215], v[184:187], v[100:103]
	v_mfma_f32_16x16x32_bf16 v[96:99], v[220:223], v[184:187], v[96:99]
	v_mfma_f32_16x16x32_bf16 v[84:87], v[212:215], v[192:195], v[84:87]
	v_mfma_f32_16x16x32_bf16 v[80:83], v[220:223], v[192:195], v[80:83]
	v_mfma_f32_16x16x32_bf16 v[68:71], v[212:215], v[200:203], v[68:71]
	v_mfma_f32_16x16x32_bf16 v[64:67], v[220:223], v[200:203], v[64:67]
	s_setprio 0
	s_mov_b32 m0, s51
	v_lshl_add_u64 v[172:173], v[224:225], 0, s[8:9]
	s_barrier
	ds_read_b128 v[168:171], v152 offset:49152
	ds_read_b128 v[176:179], v152 offset:50176
	ds_read_b128 v[180:183], v152 offset:51200
	ds_read_b128 v[184:187], v152 offset:52224
	ds_read_b128 v[188:191], v152 offset:53248
	ds_read_b128 v[192:195], v152 offset:54272
	ds_read_b128 v[196:199], v152 offset:55296
	ds_read_b128 v[200:203], v152 offset:56320
	global_load_lds_dwordx4 v[172:173], off
	v_lshl_add_u64 v[172:173], v[226:227], 0, s[8:9]
	s_mov_b32 m0, s52
	s_nop 0
	global_load_lds_dwordx4 v[172:173], off
	s_barrier
	s_waitcnt lgkmcnt(0)
	s_setprio 1
	s_waitcnt lgkmcnt(0)
	v_mfma_f32_16x16x32_bf16 v[60:63], v[144:147], v[168:171], v[60:63]
	v_mfma_f32_16x16x32_bf16 v[56:59], v[160:163], v[168:171], v[56:59]
	v_mfma_f32_16x16x32_bf16 v[44:47], v[144:147], v[180:183], v[44:47]
	v_mfma_f32_16x16x32_bf16 v[40:43], v[160:163], v[180:183], v[40:43]
	v_mfma_f32_16x16x32_bf16 v[28:31], v[144:147], v[188:191], v[28:31]
	v_mfma_f32_16x16x32_bf16 v[24:27], v[160:163], v[188:191], v[24:27]
	v_mfma_f32_16x16x32_bf16 v[12:15], v[144:147], v[196:199], v[12:15]
	v_mfma_f32_16x16x32_bf16 v[8:11], v[160:163], v[196:199], v[8:11]
	v_mfma_f32_16x16x32_bf16 v[60:63], v[156:159], v[176:179], v[60:63]
	v_mfma_f32_16x16x32_bf16 v[56:59], v[164:167], v[176:179], v[56:59]
	v_mfma_f32_16x16x32_bf16 v[44:47], v[156:159], v[184:187], v[44:47]
	v_mfma_f32_16x16x32_bf16 v[40:43], v[164:167], v[184:187], v[40:43]
	v_mfma_f32_16x16x32_bf16 v[28:31], v[156:159], v[192:195], v[28:31]
	v_mfma_f32_16x16x32_bf16 v[24:27], v[164:167], v[192:195], v[24:27]
	v_mfma_f32_16x16x32_bf16 v[12:15], v[156:159], v[200:203], v[12:15]
	v_mfma_f32_16x16x32_bf16 v[8:11], v[164:167], v[200:203], v[8:11]
	s_setprio 0
	s_barrier
	s_add_u32 s36, s36, 0x40080
	s_addc_u32 s37, s37, 0
	s_add_i32 s38, s38, s41
	v_lshl_add_u64 v[144:145], s[36:37], 0, v[130:131]
	s_mov_b32 m0, s38
	s_nop 0
	global_load_lds_dwordx4 v[144:145], off
	v_lshl_add_u64 v[144:145], s[36:37], 0, v[134:135]
	s_add_i32 m0, s38, 0x2000
	s_nop 0
	global_load_lds_dwordx4 v[144:145], off
	s_waitcnt vmcnt(6)
	s_barrier
	s_setprio 1
	v_mfma_f32_16x16x32_bf16 v[52:55], v[204:207], v[168:171], v[52:55]
	v_mfma_f32_16x16x32_bf16 v[48:51], v[216:219], v[168:171], v[48:51]
	v_mfma_f32_16x16x32_bf16 v[36:39], v[204:207], v[180:183], v[36:39]
	v_mfma_f32_16x16x32_bf16 v[32:35], v[216:219], v[180:183], v[32:35]
	v_mfma_f32_16x16x32_bf16 v[20:23], v[204:207], v[188:191], v[20:23]
	v_mfma_f32_16x16x32_bf16 v[16:19], v[216:219], v[188:191], v[16:19]
	v_mfma_f32_16x16x32_bf16 v[4:7], v[204:207], v[196:199], v[4:7]
	v_mfma_f32_16x16x32_bf16 v[0:3], v[216:219], v[196:199], v[0:3]
	v_mfma_f32_16x16x32_bf16 v[52:55], v[212:215], v[176:179], v[52:55]
	v_mfma_f32_16x16x32_bf16 v[48:51], v[220:223], v[176:179], v[48:51]
	v_mfma_f32_16x16x32_bf16 v[36:39], v[212:215], v[184:187], v[36:39]
	v_mfma_f32_16x16x32_bf16 v[32:35], v[220:223], v[184:187], v[32:35]
	v_mfma_f32_16x16x32_bf16 v[20:23], v[212:215], v[192:195], v[20:23]
	v_mfma_f32_16x16x32_bf16 v[16:19], v[220:223], v[192:195], v[16:19]
	v_mfma_f32_16x16x32_bf16 v[4:7], v[212:215], v[200:203], v[4:7]
	v_mfma_f32_16x16x32_bf16 v[0:3], v[220:223], v[200:203], v[0:3]
	s_setprio 0
	s_add_i32 s66, s66, 2
	s_add_u32 s34, s34, 0x100
	s_addc_u32 s35, s35, 0
	s_add_u32 s64, s64, 0x100
	s_addc_u32 s65, s65, 0
	s_cmp_gt_u32 s66, 13
	s_barrier
	s_cbranch_scc0 .LBB0_850
	v_lshl_add_u32 v146, s0, 8, v148
	v_ashrrev_i32_e32 v147, 31, v146
	v_lshl_add_u64 v[144:145], v[146:147], 2, s[2:3]
	global_load_dword v155, v[144:145], off
	global_load_dword v162, v[144:145], off offset:64
	global_load_dword v163, v[144:145], off offset:128
	global_load_dword v164, v[144:145], off offset:192
	global_load_dword v165, v[144:145], off offset:512
	global_load_dword v166, v[144:145], off offset:576
	global_load_dword v167, v[144:145], off offset:640
	global_load_dword v168, v[144:145], off offset:704
	v_lshl_or_b32 v144, s1, 8, v150
	v_ashrrev_i32_e32 v145, 31, v144
	v_lshlrev_b64 v[158:159], 13, v[146:147]
	v_lshlrev_b64 v[160:161], 1, v[144:145]
	v_lshl_add_u64 v[144:145], s[92:93], 0, v[158:159]
	v_lshl_add_u64 v[144:145], v[144:145], 0, v[160:161]
	v_or_b32_e32 v156, 16, v146
	v_ashrrev_i32_e32 v157, 31, v156
	v_lshlrev_b64 v[156:157], 13, v[156:157]
	v_lshl_add_u64 v[156:157], s[92:93], 0, v[156:157]
	v_lshl_add_u64 v[156:157], v[156:157], 0, v[160:161]
	s_mov_b64 s[36:37], s[30:31]
	s_mov_b64 s[34:35], s[28:29]
	s_waitcnt vmcnt(0)
	v_fmamk_f32 v147, v155, 0x3a800000, v154
	v_mul_f32_e32 v158, 0x4b800000, v147
	v_cmp_gt_f32_e32 vcc, s57, v147
	v_fmamk_f32 v155, v162, 0x3a800000, v154
	v_mul_f32_e32 v162, 0x4b800000, v155
	v_cndmask_b32_e32 v147, v147, v158, vcc
	v_rsq_f32_e32 v158, v147
	v_cmp_gt_f32_e64 s[0:1], s57, v155
	v_fmamk_f32 v159, v163, 0x3a800000, v154
	v_fmamk_f32 v163, v164, 0x3a800000, v154
	v_cndmask_b32_e64 v155, v155, v162, s[0:1]
	v_rsq_f32_e32 v155, v155
	v_mul_f32_e32 v162, 0x45800000, v158
	v_cndmask_b32_e32 v158, v158, v162, vcc
	v_pk_mul_f32 v[124:125], v[124:125], v[158:159] op_sel_hi:[1,0]
	v_pk_mul_f32 v[104:105], v[104:105], v[158:159] op_sel_hi:[1,0]
	v_fmamk_f32 v164, v165, 0x3a800000, v154
	v_fmamk_f32 v165, v166, 0x3a800000, v154
	v_fmamk_f32 v166, v167, 0x3a800000, v154
	v_mul_f32_e32 v167, 0x45800000, v155
	v_pk_mul_f32 v[126:127], v[126:127], v[158:159] op_sel_hi:[1,0]
	v_pk_mul_f32 v[122:123], v[122:123], v[158:159] op_sel_hi:[1,0]
	v_pk_mul_f32 v[120:121], v[120:121], v[158:159] op_sel_hi:[1,0]
	v_pk_mul_f32 v[108:109], v[108:109], v[158:159] op_sel_hi:[1,0]
	v_pk_mul_f32 v[106:107], v[106:107], v[158:159] op_sel_hi:[1,0]
	v_max_f32_e32 v124, 0, v124
	v_max_f32_e32 v125, 0, v125
	v_max_f32_e32 v104, 0, v104
	v_cndmask_b32_e64 v162, v155, v167, s[0:1]
	v_pk_mul_f32 v[110:111], v[110:111], v[158:159] op_sel_hi:[1,0]
	v_max_f32_e32 v120, 0, v120
	v_max_f32_e32 v121, 0, v121
	v_max_f32_e32 v126, 0, v126
	v_max_f32_e32 v122, 0, v122
	v_max_f32_e32 v127, 0, v127
	v_max_f32_e32 v123, 0, v123
	v_max_f32_e32 v108, 0, v108
	v_max_f32_e32 v109, 0, v109
	v_max_f32_e32 v105, 0, v105
	v_max_f32_e32 v106, 0, v106
	v_max_f32_e32 v107, 0, v107
	v_mul_f32_e32 v124, v124, v124
	v_mul_f32_e32 v125, v125, v125
	v_mul_f32_e32 v155, v104, v104
	v_cvt_pk_bf16_f32 v104, v124, v125
	v_fmamk_f32 v147, v168, 0x3a800000, v154
	v_pk_mul_f32 v[112:113], v[112:113], v[162:163] op_sel_hi:[1,0]
	v_max_f32_e32 v110, 0, v110
	v_max_f32_e32 v111, 0, v111
	v_mul_f32_e32 v120, v120, v120
	v_mul_f32_e32 v121, v121, v121
	v_mul_f32_e32 v126, v126, v126
	v_mul_f32_e32 v122, v122, v122
	v_mul_f32_e32 v127, v127, v127
	v_mul_f32_e32 v123, v123, v123
	v_mul_f32_e32 v108, v108, v108
	v_mul_f32_e32 v109, v109, v109
	v_mul_f32_e32 v158, v105, v105
	v_mul_f32_e32 v167, v106, v106
	v_mul_f32_e32 v168, v107, v107
	v_cvt_pk_bf16_f32 v105, v126, v127
	v_cvt_pk_bf16_f32 v106, v120, v121
	v_cvt_pk_bf16_f32 v107, v122, v123
	global_store_dwordx4 v[144:145], v[104:107], off nt
	v_pk_mul_f32 v[116:117], v[116:117], v[162:163] op_sel_hi:[1,0]
	v_mul_f32_e32 v110, v110, v110
	v_cvt_pk_bf16_f32 v104, v108, v109
	v_mul_f32_e32 v111, v111, v111
	v_cvt_pk_bf16_f32 v105, v110, v111
	v_cvt_pk_bf16_f32 v106, v155, v158
	v_cvt_pk_bf16_f32 v107, v167, v168
	global_store_dwordx4 v[144:145], v[104:107], off offset:256 nt
	v_pk_mul_f32 v[118:119], v[118:119], v[162:163] op_sel_hi:[1,0]
	v_pk_mul_f32 v[114:115], v[114:115], v[162:163] op_sel_hi:[1,0]
	v_max_f32_e32 v104, 0, v112
	v_mul_f32_e32 v106, v104, v104
	v_max_f32_e32 v104, 0, v117
	v_max_f32_e32 v116, 0, v116
	v_max_f32_e32 v107, 0, v113
	v_mul_f32_e32 v104, v104, v104
	v_pk_mul_f32 v[98:99], v[98:99], v[162:163] op_sel_hi:[1,0]
	v_pk_mul_f32 v[96:97], v[96:97], v[162:163] op_sel_hi:[1,0]
	v_mul_f32_e32 v105, v116, v116
	v_mul_f32_e32 v107, v107, v107
	v_max_f32_e32 v108, 0, v118
	v_max_f32_e32 v109, 0, v114
	v_max_f32_e32 v110, 0, v119
	v_max_f32_e32 v111, 0, v115
	v_cvt_pk_bf16_f32 v104, v105, v104
	v_pk_mul_f32 v[102:103], v[102:103], v[162:163] op_sel_hi:[1,0]
	v_pk_mul_f32 v[100:101], v[100:101], v[162:163] op_sel_hi:[1,0]
	v_max_f32_e32 v96, 0, v96
	v_max_f32_e32 v97, 0, v97
	v_max_f32_e32 v98, 0, v98
	v_mul_f32_e32 v108, v108, v108
	v_mul_f32_e32 v109, v109, v109
	v_mul_f32_e32 v110, v110, v110
	v_mul_f32_e32 v111, v111, v111
	v_cvt_pk_bf16_f32 v105, v108, v110
	v_cvt_pk_bf16_f32 v106, v106, v107
	v_cvt_pk_bf16_f32 v107, v109, v111
	global_store_dwordx4 v[156:157], v[104:107], off nt
	v_max_f32_e32 v100, 0, v100
	v_max_f32_e32 v99, 0, v99
	v_mul_f32_e32 v104, v96, v96
	v_max_f32_e32 v96, 0, v101
	v_mul_f32_e32 v101, v97, v97
	v_max_f32_e32 v97, 0, v102
	v_mul_f32_e32 v102, v98, v98
	v_max_f32_e32 v98, 0, v103
	v_mul_f32_e32 v96, v96, v96
	v_mul_f32_e32 v97, v97, v97
	v_mul_f32_e32 v98, v98, v98
	v_mul_f32_e32 v100, v100, v100
	v_mul_f32_e32 v99, v99, v99
	v_cvt_pk_bf16_f32 v96, v100, v96
	v_cvt_pk_bf16_f32 v97, v97, v98
	v_cvt_pk_bf16_f32 v98, v104, v101
	v_cvt_pk_bf16_f32 v99, v102, v99
	global_store_dwordx4 v[156:157], v[96:99], off offset:256 nt
	v_cmp_gt_f32_e32 vcc, s57, v159
	s_mov_b64 s[0:1], 0x100000
	v_mul_f32_e32 v98, 0x4b800000, v159
	v_cndmask_b32_e32 v98, v159, v98, vcc
	v_rsq_f32_e32 v98, v98
	v_or_b32_e32 v96, 32, v146
	v_ashrrev_i32_e32 v97, 31, v96
	v_lshlrev_b64 v[96:97], 13, v[96:97]
	v_mul_f32_e32 v99, 0x45800000, v98
	v_cndmask_b32_e32 v98, v98, v99, vcc
	v_pk_mul_f32 v[88:89], v[88:89], v[98:99] op_sel_hi:[1,0]
	v_pk_mul_f32 v[92:93], v[92:93], v[98:99] op_sel_hi:[1,0]
	v_pk_mul_f32 v[90:91], v[90:91], v[98:99] op_sel_hi:[1,0]
	v_max_f32_e32 v88, 0, v88
	v_pk_mul_f32 v[94:95], v[94:95], v[98:99] op_sel_hi:[1,0]
	v_mul_f32_e32 v99, v88, v88
	v_max_f32_e32 v88, 0, v93
	v_max_f32_e32 v89, 0, v89
	v_max_f32_e32 v90, 0, v90
	v_lshl_add_u64 v[96:97], s[92:93], 0, v[96:97]
	v_max_f32_e32 v92, 0, v92
	v_mul_f32_e32 v88, v88, v88
	v_mul_f32_e32 v93, v89, v89
	v_max_f32_e32 v89, 0, v94
	v_mul_f32_e32 v94, v90, v90
	v_max_f32_e32 v90, 0, v95
	v_max_f32_e32 v91, 0, v91
	v_pk_mul_f32 v[82:83], v[82:83], v[98:99] op_sel_hi:[1,0]
	v_pk_mul_f32 v[80:81], v[80:81], v[98:99] op_sel_hi:[1,0]
	v_lshl_add_u64 v[96:97], v[96:97], 0, v[160:161]
	v_mul_f32_e32 v92, v92, v92
	v_mul_f32_e32 v89, v89, v89
	v_mul_f32_e32 v90, v90, v90
	v_mul_f32_e32 v91, v91, v91
	v_cvt_pk_bf16_f32 v88, v92, v88
	v_pk_mul_f32 v[86:87], v[86:87], v[98:99] op_sel_hi:[1,0]
	v_pk_mul_f32 v[84:85], v[84:85], v[98:99] op_sel_hi:[1,0]
	v_max_f32_e32 v80, 0, v80
	v_max_f32_e32 v81, 0, v81
	v_max_f32_e32 v82, 0, v82
	v_cvt_pk_bf16_f32 v89, v89, v90
	v_cvt_pk_bf16_f32 v90, v99, v93
	v_cvt_pk_bf16_f32 v91, v94, v91
	global_store_dwordx4 v[96:97], v[88:91], off nt
	v_max_f32_e32 v84, 0, v84
	v_max_f32_e32 v83, 0, v83
	v_mul_f32_e32 v88, v80, v80
	v_max_f32_e32 v80, 0, v85
	v_mul_f32_e32 v85, v81, v81
	v_max_f32_e32 v81, 0, v86
	v_mul_f32_e32 v86, v82, v82
	v_max_f32_e32 v82, 0, v87
	v_mul_f32_e32 v80, v80, v80
	v_mul_f32_e32 v81, v81, v81
	v_mul_f32_e32 v82, v82, v82
	v_mul_f32_e32 v84, v84, v84
	v_mul_f32_e32 v83, v83, v83
	v_cvt_pk_bf16_f32 v80, v84, v80
	v_cvt_pk_bf16_f32 v81, v81, v82
	v_cvt_pk_bf16_f32 v82, v88, v85
	v_cvt_pk_bf16_f32 v83, v86, v83
	global_store_dwordx4 v[96:97], v[80:83], off offset:256 nt
	v_cmp_gt_f32_e32 vcc, s57, v163
	s_nop 0
	v_mul_f32_e32 v82, 0x4b800000, v163
	v_cndmask_b32_e32 v82, v163, v82, vcc
	v_rsq_f32_e32 v82, v82
	v_or_b32_e32 v80, 48, v146
	v_ashrrev_i32_e32 v81, 31, v80
	v_lshlrev_b64 v[80:81], 13, v[80:81]
	v_mul_f32_e32 v83, 0x45800000, v82
	v_cndmask_b32_e32 v82, v82, v83, vcc
	v_pk_mul_f32 v[72:73], v[72:73], v[82:83] op_sel_hi:[1,0]
	v_pk_mul_f32 v[76:77], v[76:77], v[82:83] op_sel_hi:[1,0]
	v_pk_mul_f32 v[74:75], v[74:75], v[82:83] op_sel_hi:[1,0]
	v_max_f32_e32 v72, 0, v72
	v_pk_mul_f32 v[78:79], v[78:79], v[82:83] op_sel_hi:[1,0]
	v_mul_f32_e32 v83, v72, v72
	v_max_f32_e32 v72, 0, v77
	v_max_f32_e32 v73, 0, v73
	v_max_f32_e32 v74, 0, v74
	v_lshl_add_u64 v[80:81], s[92:93], 0, v[80:81]
	v_max_f32_e32 v76, 0, v76
	v_mul_f32_e32 v72, v72, v72
	v_mul_f32_e32 v77, v73, v73
	v_max_f32_e32 v73, 0, v78
	v_mul_f32_e32 v78, v74, v74
	v_max_f32_e32 v74, 0, v79
	v_max_f32_e32 v75, 0, v75
	v_pk_mul_f32 v[64:65], v[64:65], v[82:83] op_sel_hi:[1,0]
	v_lshl_add_u64 v[80:81], v[80:81], 0, v[160:161]
	v_mul_f32_e32 v76, v76, v76
	v_mul_f32_e32 v73, v73, v73
	v_mul_f32_e32 v74, v74, v74
	v_mul_f32_e32 v75, v75, v75
	v_cvt_pk_bf16_f32 v72, v76, v72
	v_pk_mul_f32 v[68:69], v[68:69], v[82:83] op_sel_hi:[1,0]
	v_max_f32_e32 v64, 0, v64
	v_cvt_pk_bf16_f32 v73, v73, v74
	v_cvt_pk_bf16_f32 v74, v83, v77
	v_cvt_pk_bf16_f32 v75, v78, v75
	global_store_dwordx4 v[80:81], v[72:75], off nt
	v_max_f32_e32 v68, 0, v68
	v_mul_f32_e32 v68, v68, v68
	v_mul_f32_e32 v72, v64, v64
	v_max_f32_e32 v64, 0, v69
	v_mul_f32_e32 v64, v64, v64
	v_cvt_pk_bf16_f32 v64, v68, v64
	v_mul_f32_e32 v68, 0x4b800000, v164
	v_cmp_gt_f32_e32 vcc, s57, v164
	v_pk_mul_f32 v[66:67], v[66:67], v[82:83] op_sel_hi:[1,0]
	v_pk_mul_f32 v[70:71], v[70:71], v[82:83] op_sel_hi:[1,0]
	v_cndmask_b32_e32 v68, v164, v68, vcc
	v_max_f32_e32 v65, 0, v65
	v_max_f32_e32 v66, 0, v66
	v_rsq_f32_e32 v68, v68
	v_mul_f32_e32 v69, v65, v65
	v_max_f32_e32 v65, 0, v70
	v_mul_f32_e32 v70, v66, v66
	v_max_f32_e32 v66, 0, v71
	v_mul_f32_e32 v65, v65, v65
	v_max_f32_e32 v67, 0, v67
	v_mul_f32_e32 v66, v66, v66
	v_mul_f32_e32 v67, v67, v67
	v_cvt_pk_bf16_f32 v65, v65, v66
	v_cvt_pk_bf16_f32 v66, v72, v69
	v_cvt_pk_bf16_f32 v67, v70, v67
	global_store_dwordx4 v[80:81], v[64:67], off offset:256 nt
	s_nop 1
	v_mul_f32_e32 v66, 0x45800000, v68
	v_cndmask_b32_e32 v66, v68, v66, vcc
	v_pk_mul_f32 v[56:57], v[56:57], v[66:67] op_sel_hi:[1,0]
	v_pk_mul_f32 v[60:61], v[60:61], v[66:67] op_sel_hi:[1,0]
	v_pk_mul_f32 v[58:59], v[58:59], v[66:67] op_sel_hi:[1,0]
	v_max_f32_e32 v56, 0, v56
	v_pk_mul_f32 v[62:63], v[62:63], v[66:67] op_sel_hi:[1,0]
	v_max_f32_e32 v60, 0, v60
	v_mul_f32_e32 v67, v56, v56
	v_max_f32_e32 v56, 0, v61
	v_max_f32_e32 v57, 0, v57
	v_max_f32_e32 v58, 0, v58
	v_mul_f32_e32 v60, v60, v60
	v_mul_f32_e32 v56, v56, v56
	v_mul_f32_e32 v61, v57, v57
	v_max_f32_e32 v57, 0, v62
	v_mul_f32_e32 v62, v58, v58
	v_max_f32_e32 v58, 0, v63
	v_mul_f32_e32 v57, v57, v57
	v_max_f32_e32 v59, 0, v59
	v_mul_f32_e32 v58, v58, v58
	v_cvt_pk_bf16_f32 v56, v60, v56
	v_add_co_u32_e32 v60, vcc, s58, v144
	v_pk_mul_f32 v[48:49], v[48:49], v[66:67] op_sel_hi:[1,0]
	v_mul_f32_e32 v59, v59, v59
	v_cvt_pk_bf16_f32 v57, v57, v58
	v_cvt_pk_bf16_f32 v58, v67, v61
	v_addc_co_u32_e32 v61, vcc, 0, v145, vcc
	v_pk_mul_f32 v[52:53], v[52:53], v[66:67] op_sel_hi:[1,0]
	v_max_f32_e32 v48, 0, v48
	v_cvt_pk_bf16_f32 v59, v62, v59
	global_store_dwordx4 v[60:61], v[56:59], off nt
	v_max_f32_e32 v52, 0, v52
	v_mul_f32_e32 v52, v52, v52
	v_mul_f32_e32 v56, v48, v48
	v_max_f32_e32 v48, 0, v53
	v_mul_f32_e32 v48, v48, v48
	v_cvt_pk_bf16_f32 v48, v52, v48
	v_mul_f32_e32 v52, 0x4b800000, v165
	v_cmp_gt_f32_e32 vcc, s57, v165
	v_pk_mul_f32 v[50:51], v[50:51], v[66:67] op_sel_hi:[1,0]
	v_pk_mul_f32 v[54:55], v[54:55], v[66:67] op_sel_hi:[1,0]
	v_cndmask_b32_e32 v52, v165, v52, vcc
	v_max_f32_e32 v49, 0, v49
	v_max_f32_e32 v50, 0, v50
	v_rsq_f32_e32 v52, v52
	v_mul_f32_e32 v53, v49, v49
	v_max_f32_e32 v49, 0, v54
	v_mul_f32_e32 v54, v50, v50
	v_max_f32_e32 v50, 0, v55
	v_mul_f32_e32 v49, v49, v49
	v_max_f32_e32 v51, 0, v51
	v_mul_f32_e32 v50, v50, v50
	v_lshl_add_u64 v[64:65], v[144:145], 0, s[0:1]
	v_mul_f32_e32 v51, v51, v51
	v_cvt_pk_bf16_f32 v49, v49, v50
	v_cvt_pk_bf16_f32 v50, v56, v53
	v_cvt_pk_bf16_f32 v51, v54, v51
	global_store_dwordx4 v[64:65], v[48:51], off offset:256 nt
	s_mov_b32 s1, s24
	s_mov_b32 s0, s26
	v_mul_f32_e32 v50, 0x45800000, v52
	v_cndmask_b32_e32 v50, v52, v50, vcc
	v_pk_mul_f32 v[40:41], v[40:41], v[50:51] op_sel_hi:[1,0]
	v_pk_mul_f32 v[44:45], v[44:45], v[50:51] op_sel_hi:[1,0]
	v_pk_mul_f32 v[42:43], v[42:43], v[50:51] op_sel_hi:[1,0]
	v_max_f32_e32 v40, 0, v40
	v_pk_mul_f32 v[46:47], v[46:47], v[50:51] op_sel_hi:[1,0]
	v_max_f32_e32 v44, 0, v44
	v_mul_f32_e32 v51, v40, v40
	v_max_f32_e32 v40, 0, v45
	v_max_f32_e32 v41, 0, v41
	v_max_f32_e32 v42, 0, v42
	v_mul_f32_e32 v44, v44, v44
	v_mul_f32_e32 v40, v40, v40
	v_mul_f32_e32 v45, v41, v41
	v_max_f32_e32 v41, 0, v46
	v_mul_f32_e32 v46, v42, v42
	v_max_f32_e32 v42, 0, v47
	v_mul_f32_e32 v41, v41, v41
	v_max_f32_e32 v43, 0, v43
	v_mul_f32_e32 v42, v42, v42
	v_cvt_pk_bf16_f32 v40, v44, v40
	v_add_co_u32_e32 v44, vcc, s59, v144
	v_pk_mul_f32 v[32:33], v[32:33], v[50:51] op_sel_hi:[1,0]
	v_mul_f32_e32 v43, v43, v43
	v_cvt_pk_bf16_f32 v41, v41, v42
	v_cvt_pk_bf16_f32 v42, v51, v45
	v_addc_co_u32_e32 v45, vcc, 0, v145, vcc
	v_pk_mul_f32 v[36:37], v[36:37], v[50:51] op_sel_hi:[1,0]
	v_max_f32_e32 v32, 0, v32
	v_cvt_pk_bf16_f32 v43, v46, v43
	global_store_dwordx4 v[44:45], v[40:43], off nt
	v_max_f32_e32 v36, 0, v36
	v_mul_f32_e32 v36, v36, v36
	v_mul_f32_e32 v40, v32, v32
	v_max_f32_e32 v32, 0, v37
	v_mul_f32_e32 v32, v32, v32
	v_cvt_pk_bf16_f32 v32, v36, v32
	v_mul_f32_e32 v36, 0x4b800000, v166
	v_cmp_gt_f32_e32 vcc, s57, v166
	v_pk_mul_f32 v[34:35], v[34:35], v[50:51] op_sel_hi:[1,0]
	v_pk_mul_f32 v[38:39], v[38:39], v[50:51] op_sel_hi:[1,0]
	v_cndmask_b32_e32 v36, v166, v36, vcc
	v_max_f32_e32 v33, 0, v33
	v_max_f32_e32 v34, 0, v34
	v_rsq_f32_e32 v36, v36
	v_mul_f32_e32 v37, v33, v33
	v_max_f32_e32 v33, 0, v38
	v_mul_f32_e32 v38, v34, v34
	v_max_f32_e32 v34, 0, v39
	v_mul_f32_e32 v33, v33, v33
	v_max_f32_e32 v35, 0, v35
	v_mul_f32_e32 v34, v34, v34
	v_lshl_add_u64 v[48:49], v[144:145], 0, s[18:19]
	v_mul_f32_e32 v35, v35, v35
	v_cvt_pk_bf16_f32 v33, v33, v34
	v_cvt_pk_bf16_f32 v34, v40, v37
	v_cvt_pk_bf16_f32 v35, v38, v35
	global_store_dwordx4 v[48:49], v[32:35], off offset:256 nt
	s_nop 1
	v_mul_f32_e32 v34, 0x45800000, v36
	v_cndmask_b32_e32 v34, v36, v34, vcc
	v_pk_mul_f32 v[24:25], v[24:25], v[34:35] op_sel_hi:[1,0]
	v_pk_mul_f32 v[28:29], v[28:29], v[34:35] op_sel_hi:[1,0]
	v_pk_mul_f32 v[26:27], v[26:27], v[34:35] op_sel_hi:[1,0]
	v_max_f32_e32 v24, 0, v24
	v_pk_mul_f32 v[30:31], v[30:31], v[34:35] op_sel_hi:[1,0]
	v_max_f32_e32 v28, 0, v28
	v_mul_f32_e32 v35, v24, v24
	v_max_f32_e32 v24, 0, v29
	v_max_f32_e32 v25, 0, v25
	v_max_f32_e32 v26, 0, v26
	v_mul_f32_e32 v28, v28, v28
	v_mul_f32_e32 v24, v24, v24
	v_mul_f32_e32 v29, v25, v25
	v_max_f32_e32 v25, 0, v30
	v_mul_f32_e32 v30, v26, v26
	v_max_f32_e32 v26, 0, v31
	v_mul_f32_e32 v25, v25, v25
	v_max_f32_e32 v27, 0, v27
	v_mul_f32_e32 v26, v26, v26
	v_cvt_pk_bf16_f32 v24, v28, v24
	v_add_co_u32_e32 v28, vcc, s60, v144
	v_pk_mul_f32 v[16:17], v[16:17], v[34:35] op_sel_hi:[1,0]
	v_mul_f32_e32 v27, v27, v27
	v_cvt_pk_bf16_f32 v25, v25, v26
	v_cvt_pk_bf16_f32 v26, v35, v29
	v_addc_co_u32_e32 v29, vcc, 0, v145, vcc
	v_pk_mul_f32 v[20:21], v[20:21], v[34:35] op_sel_hi:[1,0]
	v_max_f32_e32 v16, 0, v16
	v_cvt_pk_bf16_f32 v27, v30, v27
	global_store_dwordx4 v[28:29], v[24:27], off nt
	v_max_f32_e32 v20, 0, v20
	v_mul_f32_e32 v20, v20, v20
	v_mul_f32_e32 v24, v16, v16
	v_max_f32_e32 v16, 0, v21
	v_mul_f32_e32 v16, v16, v16
	v_cvt_pk_bf16_f32 v16, v20, v16
	v_mul_f32_e32 v20, 0x4b800000, v147
	v_cmp_gt_f32_e32 vcc, s57, v147
	v_pk_mul_f32 v[18:19], v[18:19], v[34:35] op_sel_hi:[1,0]
	v_pk_mul_f32 v[22:23], v[22:23], v[34:35] op_sel_hi:[1,0]
	v_cndmask_b32_e32 v20, v147, v20, vcc
	v_max_f32_e32 v17, 0, v17
	v_max_f32_e32 v18, 0, v18
	v_rsq_f32_e32 v20, v20
	v_mul_f32_e32 v21, v17, v17
	v_max_f32_e32 v17, 0, v22
	v_mul_f32_e32 v22, v18, v18
	v_max_f32_e32 v18, 0, v23
	v_mul_f32_e32 v17, v17, v17
	v_max_f32_e32 v19, 0, v19
	v_mul_f32_e32 v18, v18, v18
	v_lshl_add_u64 v[32:33], v[144:145], 0, s[20:21]
	v_mul_f32_e32 v19, v19, v19
	v_cvt_pk_bf16_f32 v17, v17, v18
	v_cvt_pk_bf16_f32 v18, v24, v21
	v_cvt_pk_bf16_f32 v19, v22, v19
	global_store_dwordx4 v[32:33], v[16:19], off offset:256 nt
	s_nop 1
	v_mul_f32_e32 v18, 0x45800000, v20
	v_cndmask_b32_e32 v18, v20, v18, vcc
	v_pk_mul_f32 v[8:9], v[8:9], v[18:19] op_sel_hi:[1,0]
	v_pk_mul_f32 v[12:13], v[12:13], v[18:19] op_sel_hi:[1,0]
	v_pk_mul_f32 v[10:11], v[10:11], v[18:19] op_sel_hi:[1,0]
	v_max_f32_e32 v8, 0, v8
	v_pk_mul_f32 v[14:15], v[14:15], v[18:19] op_sel_hi:[1,0]
	v_max_f32_e32 v12, 0, v12
	v_mul_f32_e32 v19, v8, v8
	v_max_f32_e32 v8, 0, v13
	v_max_f32_e32 v9, 0, v9
	v_max_f32_e32 v10, 0, v10
	v_mul_f32_e32 v12, v12, v12
	v_mul_f32_e32 v8, v8, v8
	v_mul_f32_e32 v13, v9, v9
	v_max_f32_e32 v9, 0, v14
	v_mul_f32_e32 v14, v10, v10
	v_max_f32_e32 v10, 0, v15
	v_mul_f32_e32 v9, v9, v9
	v_max_f32_e32 v11, 0, v11
	v_mul_f32_e32 v10, v10, v10
	v_cvt_pk_bf16_f32 v8, v12, v8
	v_add_co_u32_e32 v12, vcc, s61, v144
	v_pk_mul_f32 v[2:3], v[2:3], v[18:19] op_sel_hi:[1,0]
	v_pk_mul_f32 v[0:1], v[0:1], v[18:19] op_sel_hi:[1,0]
	v_mul_f32_e32 v11, v11, v11
	v_cvt_pk_bf16_f32 v9, v9, v10
	v_cvt_pk_bf16_f32 v10, v19, v13
	v_addc_co_u32_e32 v13, vcc, 0, v145, vcc
	v_pk_mul_f32 v[6:7], v[6:7], v[18:19] op_sel_hi:[1,0]
	v_pk_mul_f32 v[4:5], v[4:5], v[18:19] op_sel_hi:[1,0]
	v_max_f32_e32 v0, 0, v0
	v_max_f32_e32 v1, 0, v1
	v_max_f32_e32 v2, 0, v2
	v_cvt_pk_bf16_f32 v11, v14, v11
	global_store_dwordx4 v[12:13], v[8:11], off nt
	v_max_f32_e32 v3, 0, v3
	v_lshl_add_u64 v[16:17], v[144:145], 0, s[22:23]
	v_mul_f32_e32 v8, v0, v0
	v_max_f32_e32 v0, 0, v5
	v_mul_f32_e32 v5, v1, v1
	v_max_f32_e32 v1, 0, v6
	v_mul_f32_e32 v6, v2, v2
	v_max_f32_e32 v2, 0, v7
	v_max_f32_e32 v4, 0, v4
	v_mul_f32_e32 v0, v0, v0
	v_mul_f32_e32 v1, v1, v1
	v_mul_f32_e32 v2, v2, v2
	v_mul_f32_e32 v3, v3, v3
	s_and_b64 vcc, exec, s[6:7]
	v_mul_f32_e32 v4, v4, v4
	v_cvt_pk_bf16_f32 v0, v4, v0
	v_cvt_pk_bf16_f32 v1, v1, v2
	v_cvt_pk_bf16_f32 v2, v8, v5
	v_cvt_pk_bf16_f32 v3, v6, v3
	global_store_dwordx4 v[16:17], v[0:3], off offset:256 nt
	s_cbranch_vccz .LBB0_843
	s_waitcnt vmcnt(0)
	s_cmpk_gt_u32 s33, 0xff
	s_cbranch_scc1 .LBB0_854
	s_barrier

.LBB0_1218:
	ds_read_b128 v[144:147], v151
	ds_read_b128 v[156:159], v151 offset:1024
	ds_read_b128 v[160:163], v151 offset:2048
	ds_read_b128 v[164:167], v151 offset:3072
	s_add_u32 s30, s28, 0xfffc0080
	s_addc_u32 s31, s29, -1
	s_cmp_eq_u32 s63, 12
	s_cselect_b32 s35, s23, s31
	s_cselect_b32 s34, s59, s30
	s_cselect_b32 s31, s21, s62
	s_cselect_b32 s30, s60, s61
	v_lshl_add_u64 v[172:173], s[28:29], 0, v[136:137]
	s_add_i32 m0, s40, 0xc000
	ds_read_b128 v[168:171], v152
	ds_read_b128 v[176:179], v152 offset:1024
	ds_read_b128 v[180:183], v152 offset:2048
	ds_read_b128 v[184:187], v152 offset:3072
	ds_read_b128 v[188:191], v152 offset:4096
	ds_read_b128 v[192:195], v152 offset:5120
	ds_read_b128 v[196:199], v152 offset:6144
	ds_read_b128 v[200:203], v152 offset:7168
	global_load_lds_dwordx4 v[172:173], off
	v_lshl_add_u64 v[172:173], s[28:29], 0, v[138:139]
	s_add_i32 m0, s40, 0xe000
	s_nop 0
	global_load_lds_dwordx4 v[172:173], off
	s_waitcnt lgkmcnt(8)
	s_barrier
	s_waitcnt lgkmcnt(0)
	s_setprio 1
	s_waitcnt lgkmcnt(0)
	v_mfma_f32_16x16x32_bf16 v[124:127], v[144:147], v[168:171], v[124:127]
	v_mfma_f32_16x16x32_bf16 v[120:123], v[160:163], v[168:171], v[120:123]
	v_mfma_f32_16x16x32_bf16 v[116:119], v[144:147], v[180:183], v[116:119]
	v_mfma_f32_16x16x32_bf16 v[112:115], v[160:163], v[180:183], v[112:115]
	v_mfma_f32_16x16x32_bf16 v[92:95], v[144:147], v[188:191], v[92:95]
	v_mfma_f32_16x16x32_bf16 v[88:91], v[160:163], v[188:191], v[88:91]
	v_mfma_f32_16x16x32_bf16 v[76:79], v[144:147], v[196:199], v[76:79]
	v_mfma_f32_16x16x32_bf16 v[72:75], v[160:163], v[196:199], v[72:75]
	v_mfma_f32_16x16x32_bf16 v[124:127], v[156:159], v[176:179], v[124:127]
	v_mfma_f32_16x16x32_bf16 v[120:123], v[164:167], v[176:179], v[120:123]
	v_mfma_f32_16x16x32_bf16 v[116:119], v[156:159], v[184:187], v[116:119]
	v_mfma_f32_16x16x32_bf16 v[112:115], v[164:167], v[184:187], v[112:115]
	v_mfma_f32_16x16x32_bf16 v[92:95], v[156:159], v[192:195], v[92:95]
	v_mfma_f32_16x16x32_bf16 v[88:91], v[164:167], v[192:195], v[88:91]
	v_mfma_f32_16x16x32_bf16 v[76:79], v[156:159], v[200:203], v[76:79]
	v_mfma_f32_16x16x32_bf16 v[72:75], v[164:167], v[200:203], v[72:75]
	s_setprio 0
	s_barrier
	s_add_i32 s64, s52, s39
	v_lshl_add_u64 v[172:173], s[30:31], 0, v[130:131]
	s_mov_b32 m0, s64
	ds_read_b128 v[204:207], v153
	ds_read_b128 v[212:215], v153 offset:1024
	ds_read_b128 v[216:219], v153 offset:2048
	ds_read_b128 v[220:223], v153 offset:3072
	global_load_lds_dwordx4 v[172:173], off
	v_lshl_add_u64 v[208:209], s[30:31], 0, v[134:135]
	s_add_i32 m0, s64, 0x2000
	s_nop 0
	global_load_lds_dwordx4 v[208:209], off
	s_barrier
	s_waitcnt lgkmcnt(0)
	s_setprio 1
	s_waitcnt lgkmcnt(0)
	v_mfma_f32_16x16x32_bf16 v[108:111], v[204:207], v[168:171], v[108:111]
	v_mfma_f32_16x16x32_bf16 v[104:107], v[216:219], v[168:171], v[104:107]
	v_mfma_f32_16x16x32_bf16 v[100:103], v[204:207], v[180:183], v[100:103]
	v_mfma_f32_16x16x32_bf16 v[96:99], v[216:219], v[180:183], v[96:99]
	v_mfma_f32_16x16x32_bf16 v[84:87], v[204:207], v[188:191], v[84:87]
	v_mfma_f32_16x16x32_bf16 v[80:83], v[216:219], v[188:191], v[80:83]
	v_mfma_f32_16x16x32_bf16 v[68:71], v[204:207], v[196:199], v[68:71]
	v_mfma_f32_16x16x32_bf16 v[64:67], v[216:219], v[196:199], v[64:67]
	v_mfma_f32_16x16x32_bf16 v[108:111], v[212:215], v[176:179], v[108:111]
	v_mfma_f32_16x16x32_bf16 v[104:107], v[220:223], v[176:179], v[104:107]
	v_mfma_f32_16x16x32_bf16 v[100:103], v[212:215], v[184:187], v[100:103]
	v_mfma_f32_16x16x32_bf16 v[96:99], v[220:223], v[184:187], v[96:99]
	v_mfma_f32_16x16x32_bf16 v[84:87], v[212:215], v[192:195], v[84:87]
	v_mfma_f32_16x16x32_bf16 v[80:83], v[220:223], v[192:195], v[80:83]
	v_mfma_f32_16x16x32_bf16 v[68:71], v[212:215], v[200:203], v[68:71]
	v_mfma_f32_16x16x32_bf16 v[64:67], v[220:223], v[200:203], v[64:67]
	s_setprio 0
	s_mov_b32 m0, s40
	v_lshl_add_u64 v[224:225], s[34:35], 0, v[128:129]
	s_barrier
	ds_read_b128 v[168:171], v152 offset:16384
	ds_read_b128 v[176:179], v152 offset:17408
	ds_read_b128 v[180:183], v152 offset:18432
	ds_read_b128 v[184:187], v152 offset:19456
	ds_read_b128 v[188:191], v152 offset:20480
	ds_read_b128 v[192:195], v152 offset:21504
	ds_read_b128 v[196:199], v152 offset:22528
	ds_read_b128 v[200:203], v152 offset:23552
	global_load_lds_dwordx4 v[224:225], off
	v_lshl_add_u64 v[226:227], s[34:35], 0, v[132:133]
	s_mov_b32 m0, s41
	s_nop 0
	global_load_lds_dwordx4 v[226:227], off
	s_barrier
	s_waitcnt lgkmcnt(0)
	s_setprio 1
	s_waitcnt lgkmcnt(0)
	v_mfma_f32_16x16x32_bf16 v[60:63], v[144:147], v[168:171], v[60:63]
	v_mfma_f32_16x16x32_bf16 v[56:59], v[160:163], v[168:171], v[56:59]
	v_mfma_f32_16x16x32_bf16 v[44:47], v[144:147], v[180:183], v[44:47]
	v_mfma_f32_16x16x32_bf16 v[40:43], v[160:163], v[180:183], v[40:43]
	v_mfma_f32_16x16x32_bf16 v[28:31], v[144:147], v[188:191], v[28:31]
	v_mfma_f32_16x16x32_bf16 v[24:27], v[160:163], v[188:191], v[24:27]
	v_mfma_f32_16x16x32_bf16 v[12:15], v[144:147], v[196:199], v[12:15]
	v_mfma_f32_16x16x32_bf16 v[8:11], v[160:163], v[196:199], v[8:11]
	v_mfma_f32_16x16x32_bf16 v[60:63], v[156:159], v[176:179], v[60:63]
	v_mfma_f32_16x16x32_bf16 v[56:59], v[164:167], v[176:179], v[56:59]
	v_mfma_f32_16x16x32_bf16 v[44:47], v[156:159], v[184:187], v[44:47]
	v_mfma_f32_16x16x32_bf16 v[40:43], v[164:167], v[184:187], v[40:43]
	v_mfma_f32_16x16x32_bf16 v[28:31], v[156:159], v[192:195], v[28:31]
	v_mfma_f32_16x16x32_bf16 v[24:27], v[164:167], v[192:195], v[24:27]
	v_mfma_f32_16x16x32_bf16 v[12:15], v[156:159], v[200:203], v[12:15]
	v_mfma_f32_16x16x32_bf16 v[8:11], v[164:167], v[200:203], v[8:11]
	s_setprio 0
	s_barrier
	s_add_u32 s64, s30, 0x40000
	s_addc_u32 s65, s31, 0
	s_add_i32 s66, s53, s39
	v_lshl_add_u64 v[144:145], s[64:65], 0, v[130:131]
	s_mov_b32 m0, s66
	s_nop 0
	global_load_lds_dwordx4 v[144:145], off
	v_lshl_add_u64 v[144:145], s[64:65], 0, v[134:135]
	s_add_i32 m0, s66, 0x2000
	s_nop 0
	global_load_lds_dwordx4 v[144:145], off
	s_waitcnt vmcnt(6)
	s_barrier
	s_setprio 1
	v_mfma_f32_16x16x32_bf16 v[52:55], v[204:207], v[168:171], v[52:55]
	v_mfma_f32_16x16x32_bf16 v[48:51], v[216:219], v[168:171], v[48:51]
	v_mfma_f32_16x16x32_bf16 v[36:39], v[204:207], v[180:183], v[36:39]
	v_mfma_f32_16x16x32_bf16 v[32:35], v[216:219], v[180:183], v[32:35]
	v_mfma_f32_16x16x32_bf16 v[20:23], v[204:207], v[188:191], v[20:23]
	v_mfma_f32_16x16x32_bf16 v[16:19], v[216:219], v[188:191], v[16:19]
	v_mfma_f32_16x16x32_bf16 v[4:7], v[204:207], v[196:199], v[4:7]
	v_mfma_f32_16x16x32_bf16 v[0:3], v[216:219], v[196:199], v[0:3]
	v_mfma_f32_16x16x32_bf16 v[52:55], v[212:215], v[176:179], v[52:55]
	v_mfma_f32_16x16x32_bf16 v[48:51], v[220:223], v[176:179], v[48:51]
	v_mfma_f32_16x16x32_bf16 v[36:39], v[212:215], v[184:187], v[36:39]
	v_mfma_f32_16x16x32_bf16 v[32:35], v[220:223], v[184:187], v[32:35]
	v_mfma_f32_16x16x32_bf16 v[20:23], v[212:215], v[192:195], v[20:23]
	v_mfma_f32_16x16x32_bf16 v[16:19], v[220:223], v[192:195], v[16:19]
	v_mfma_f32_16x16x32_bf16 v[4:7], v[212:215], v[200:203], v[4:7]
	v_mfma_f32_16x16x32_bf16 v[0:3], v[220:223], v[200:203], v[0:3]
	s_setprio 0
	s_add_i32 s64, 0, 0x18000
	v_add_u32_e32 v155, s64, v149
	s_barrier
	ds_read_b128 v[144:147], v155
	ds_read_b128 v[156:159], v155 offset:1024
	ds_read_b128 v[160:163], v155 offset:2048
	ds_read_b128 v[164:167], v155 offset:3072
	s_add_u32 s34, s34, 0x40000
	s_addc_u32 s35, s35, 0
	s_mov_b32 m0, s42
	v_lshl_add_u64 v[204:205], s[34:35], 0, v[128:129]
	ds_read_b128 v[168:171], v152 offset:32768
	ds_read_b128 v[176:179], v152 offset:33792
	ds_read_b128 v[180:183], v152 offset:34816
	ds_read_b128 v[184:187], v152 offset:35840
	ds_read_b128 v[188:191], v152 offset:36864
	ds_read_b128 v[192:195], v152 offset:37888
	ds_read_b128 v[196:199], v152 offset:38912
	ds_read_b128 v[200:203], v152 offset:39936
	global_load_lds_dwordx4 v[204:205], off
	v_lshl_add_u64 v[204:205], s[34:35], 0, v[132:133]
	s_mov_b32 m0, s43
	s_nop 0
	global_load_lds_dwordx4 v[204:205], off
	s_waitcnt lgkmcnt(8)
	s_barrier
	s_waitcnt lgkmcnt(0)
	s_setprio 1
	s_waitcnt lgkmcnt(0)
	v_mfma_f32_16x16x32_bf16 v[124:127], v[144:147], v[168:171], v[124:127]
	v_mfma_f32_16x16x32_bf16 v[120:123], v[160:163], v[168:171], v[120:123]
	v_mfma_f32_16x16x32_bf16 v[116:119], v[144:147], v[180:183], v[116:119]
	v_mfma_f32_16x16x32_bf16 v[112:115], v[160:163], v[180:183], v[112:115]
	v_mfma_f32_16x16x32_bf16 v[92:95], v[144:147], v[188:191], v[92:95]
	v_mfma_f32_16x16x32_bf16 v[88:91], v[160:163], v[188:191], v[88:91]
	v_mfma_f32_16x16x32_bf16 v[76:79], v[144:147], v[196:199], v[76:79]
	v_mfma_f32_16x16x32_bf16 v[72:75], v[160:163], v[196:199], v[72:75]
	v_mfma_f32_16x16x32_bf16 v[124:127], v[156:159], v[176:179], v[124:127]
	v_mfma_f32_16x16x32_bf16 v[120:123], v[164:167], v[176:179], v[120:123]
	v_mfma_f32_16x16x32_bf16 v[116:119], v[156:159], v[184:187], v[116:119]
	v_mfma_f32_16x16x32_bf16 v[112:115], v[164:167], v[184:187], v[112:115]
	v_mfma_f32_16x16x32_bf16 v[92:95], v[156:159], v[192:195], v[92:95]
	v_mfma_f32_16x16x32_bf16 v[88:91], v[164:167], v[192:195], v[88:91]
	v_mfma_f32_16x16x32_bf16 v[76:79], v[156:159], v[200:203], v[76:79]
	v_mfma_f32_16x16x32_bf16 v[72:75], v[164:167], v[200:203], v[72:75]
	s_setprio 0
	s_barrier
	s_add_i32 s34, 0, 0x1c000
	s_add_i32 s35, s64, s39
	v_add_u32_e32 v155, s34, v149
	v_lshl_add_u64 v[172:173], v[172:173], 0, s[6:7]
	s_mov_b32 m0, s35
	ds_read_b128 v[204:207], v155
	ds_read_b128 v[212:215], v155 offset:1024
	ds_read_b128 v[216:219], v155 offset:2048
	ds_read_b128 v[220:223], v155 offset:3072
	global_load_lds_dwordx4 v[172:173], off
	v_lshl_add_u64 v[172:173], v[208:209], 0, s[6:7]
	s_add_i32 m0, s35, 0x2000
	s_nop 0
	global_load_lds_dwordx4 v[172:173], off
	s_barrier
	s_waitcnt lgkmcnt(0)
	s_setprio 1
	s_waitcnt lgkmcnt(0)
	v_mfma_f32_16x16x32_bf16 v[108:111], v[204:207], v[168:171], v[108:111]
	v_mfma_f32_16x16x32_bf16 v[104:107], v[216:219], v[168:171], v[104:107]
	v_mfma_f32_16x16x32_bf16 v[100:103], v[204:207], v[180:183], v[100:103]
	v_mfma_f32_16x16x32_bf16 v[96:99], v[216:219], v[180:183], v[96:99]
	v_mfma_f32_16x16x32_bf16 v[84:87], v[204:207], v[188:191], v[84:87]
	v_mfma_f32_16x16x32_bf16 v[80:83], v[216:219], v[188:191], v[80:83]
	v_mfma_f32_16x16x32_bf16 v[68:71], v[204:207], v[196:199], v[68:71]
	v_mfma_f32_16x16x32_bf16 v[64:67], v[216:219], v[196:199], v[64:67]
	v_mfma_f32_16x16x32_bf16 v[108:111], v[212:215], v[176:179], v[108:111]
	v_mfma_f32_16x16x32_bf16 v[104:107], v[220:223], v[176:179], v[104:107]
	v_mfma_f32_16x16x32_bf16 v[100:103], v[212:215], v[184:187], v[100:103]
	v_mfma_f32_16x16x32_bf16 v[96:99], v[220:223], v[184:187], v[96:99]
	v_mfma_f32_16x16x32_bf16 v[84:87], v[212:215], v[192:195], v[84:87]
	v_mfma_f32_16x16x32_bf16 v[80:83], v[220:223], v[192:195], v[80:83]
	v_mfma_f32_16x16x32_bf16 v[68:71], v[212:215], v[200:203], v[68:71]
	v_mfma_f32_16x16x32_bf16 v[64:67], v[220:223], v[200:203], v[64:67]
	s_setprio 0
	s_mov_b32 m0, s49
	v_lshl_add_u64 v[172:173], v[224:225], 0, s[6:7]
	s_barrier
	ds_read_b128 v[168:171], v152 offset:49152
	ds_read_b128 v[176:179], v152 offset:50176
	ds_read_b128 v[180:183], v152 offset:51200
	ds_read_b128 v[184:187], v152 offset:52224
	ds_read_b128 v[188:191], v152 offset:53248
	ds_read_b128 v[192:195], v152 offset:54272
	ds_read_b128 v[196:199], v152 offset:55296
	ds_read_b128 v[200:203], v152 offset:56320
	global_load_lds_dwordx4 v[172:173], off
	v_lshl_add_u64 v[172:173], v[226:227], 0, s[6:7]
	s_mov_b32 m0, s50
	s_nop 0
	global_load_lds_dwordx4 v[172:173], off
	s_barrier
	s_waitcnt lgkmcnt(0)
	s_setprio 1
	s_waitcnt lgkmcnt(0)
	v_mfma_f32_16x16x32_bf16 v[60:63], v[144:147], v[168:171], v[60:63]
	v_mfma_f32_16x16x32_bf16 v[56:59], v[160:163], v[168:171], v[56:59]
	v_mfma_f32_16x16x32_bf16 v[44:47], v[144:147], v[180:183], v[44:47]
	v_mfma_f32_16x16x32_bf16 v[40:43], v[160:163], v[180:183], v[40:43]
	v_mfma_f32_16x16x32_bf16 v[28:31], v[144:147], v[188:191], v[28:31]
	v_mfma_f32_16x16x32_bf16 v[24:27], v[160:163], v[188:191], v[24:27]
	v_mfma_f32_16x16x32_bf16 v[12:15], v[144:147], v[196:199], v[12:15]
	v_mfma_f32_16x16x32_bf16 v[8:11], v[160:163], v[196:199], v[8:11]
	v_mfma_f32_16x16x32_bf16 v[60:63], v[156:159], v[176:179], v[60:63]
	v_mfma_f32_16x16x32_bf16 v[56:59], v[164:167], v[176:179], v[56:59]
	v_mfma_f32_16x16x32_bf16 v[44:47], v[156:159], v[184:187], v[44:47]
	v_mfma_f32_16x16x32_bf16 v[40:43], v[164:167], v[184:187], v[40:43]
	v_mfma_f32_16x16x32_bf16 v[28:31], v[156:159], v[192:195], v[28:31]
	v_mfma_f32_16x16x32_bf16 v[24:27], v[164:167], v[192:195], v[24:27]
	v_mfma_f32_16x16x32_bf16 v[12:15], v[156:159], v[200:203], v[12:15]
	v_mfma_f32_16x16x32_bf16 v[8:11], v[164:167], v[200:203], v[8:11]
	s_setprio 0
	s_barrier
	s_add_u32 s30, s30, 0x40080
	s_addc_u32 s31, s31, 0
	s_add_i32 s34, s34, s39
	v_lshl_add_u64 v[144:145], s[30:31], 0, v[130:131]
	s_mov_b32 m0, s34
	s_nop 0
	global_load_lds_dwordx4 v[144:145], off
	v_lshl_add_u64 v[144:145], s[30:31], 0, v[134:135]
	s_add_i32 m0, s34, 0x2000
	s_nop 0
	global_load_lds_dwordx4 v[144:145], off
	s_waitcnt vmcnt(6)
	s_barrier
	s_setprio 1
	v_mfma_f32_16x16x32_bf16 v[52:55], v[204:207], v[168:171], v[52:55]
	v_mfma_f32_16x16x32_bf16 v[48:51], v[216:219], v[168:171], v[48:51]
	v_mfma_f32_16x16x32_bf16 v[36:39], v[204:207], v[180:183], v[36:39]
	v_mfma_f32_16x16x32_bf16 v[32:35], v[216:219], v[180:183], v[32:35]
	v_mfma_f32_16x16x32_bf16 v[20:23], v[204:207], v[188:191], v[20:23]
	v_mfma_f32_16x16x32_bf16 v[16:19], v[216:219], v[188:191], v[16:19]
	v_mfma_f32_16x16x32_bf16 v[4:7], v[204:207], v[196:199], v[4:7]
	v_mfma_f32_16x16x32_bf16 v[0:3], v[216:219], v[196:199], v[0:3]
	v_mfma_f32_16x16x32_bf16 v[52:55], v[212:215], v[176:179], v[52:55]
	v_mfma_f32_16x16x32_bf16 v[48:51], v[220:223], v[176:179], v[48:51]
	v_mfma_f32_16x16x32_bf16 v[36:39], v[212:215], v[184:187], v[36:39]
	v_mfma_f32_16x16x32_bf16 v[32:35], v[220:223], v[184:187], v[32:35]
	v_mfma_f32_16x16x32_bf16 v[20:23], v[212:215], v[192:195], v[20:23]
	v_mfma_f32_16x16x32_bf16 v[16:19], v[220:223], v[192:195], v[16:19]
	v_mfma_f32_16x16x32_bf16 v[4:7], v[212:215], v[200:203], v[4:7]
	v_mfma_f32_16x16x32_bf16 v[0:3], v[220:223], v[200:203], v[0:3]
	s_setprio 0
	s_add_i32 s63, s63, 2
	s_add_u32 s28, s28, 0x100
	s_addc_u32 s29, s29, 0
	s_add_u32 s61, s61, 0x100
	s_addc_u32 s62, s62, 0
	s_cmp_gt_u32 s63, 13
	s_barrier
	s_cbranch_scc0 .LBB0_1218
	v_lshl_add_u32 v146, s0, 8, v148
	v_ashrrev_i32_e32 v147, 31, v146
	v_lshl_add_u64 v[144:145], v[146:147], 2, s[8:9]
	global_load_dword v155, v[144:145], off
	global_load_dword v162, v[144:145], off offset:64
	global_load_dword v163, v[144:145], off offset:128
	global_load_dword v164, v[144:145], off offset:192
	global_load_dword v165, v[144:145], off offset:512
	global_load_dword v166, v[144:145], off offset:576
	global_load_dword v167, v[144:145], off offset:640
	global_load_dword v168, v[144:145], off offset:704
	v_lshl_or_b32 v144, s1, 8, v150
	v_ashrrev_i32_e32 v145, 31, v144
	v_lshlrev_b64 v[158:159], 13, v[146:147]
	v_lshlrev_b64 v[160:161], 1, v[144:145]
	v_lshl_add_u64 v[144:145], s[92:93], 0, v[158:159]
	v_lshl_add_u64 v[144:145], v[144:145], 0, v[160:161]
	v_or_b32_e32 v156, 16, v146
	v_ashrrev_i32_e32 v157, 31, v156
	v_lshlrev_b64 v[156:157], 13, v[156:157]
	v_lshl_add_u64 v[156:157], s[92:93], 0, v[156:157]
	v_lshl_add_u64 v[156:157], v[156:157], 0, v[160:161]
	s_mov_b64 s[30:31], s[26:27]
	s_mov_b64 s[28:29], s[24:25]
	s_waitcnt vmcnt(0)
	v_fmamk_f32 v147, v155, 0x3a800000, v154
	v_mul_f32_e32 v158, 0x4b800000, v147
	v_cmp_gt_f32_e32 vcc, s54, v147
	v_fmamk_f32 v155, v162, 0x3a800000, v154
	v_mul_f32_e32 v162, 0x4b800000, v155
	v_cndmask_b32_e32 v147, v147, v158, vcc
	v_rsq_f32_e32 v158, v147
	v_cmp_gt_f32_e64 s[0:1], s54, v155
	v_fmamk_f32 v159, v163, 0x3a800000, v154
	v_fmamk_f32 v163, v164, 0x3a800000, v154
	v_cndmask_b32_e64 v155, v155, v162, s[0:1]
	v_rsq_f32_e32 v155, v155
	v_mul_f32_e32 v162, 0x45800000, v158
	v_cndmask_b32_e32 v158, v158, v162, vcc
	v_pk_mul_f32 v[124:125], v[124:125], v[158:159] op_sel_hi:[1,0]
	v_pk_mul_f32 v[104:105], v[104:105], v[158:159] op_sel_hi:[1,0]
	v_fmamk_f32 v164, v165, 0x3a800000, v154
	v_fmamk_f32 v165, v166, 0x3a800000, v154
	v_fmamk_f32 v166, v167, 0x3a800000, v154
	v_mul_f32_e32 v167, 0x45800000, v155
	v_pk_mul_f32 v[126:127], v[126:127], v[158:159] op_sel_hi:[1,0]
	v_pk_mul_f32 v[122:123], v[122:123], v[158:159] op_sel_hi:[1,0]
	v_pk_mul_f32 v[120:121], v[120:121], v[158:159] op_sel_hi:[1,0]
	v_pk_mul_f32 v[108:109], v[108:109], v[158:159] op_sel_hi:[1,0]
	v_pk_mul_f32 v[106:107], v[106:107], v[158:159] op_sel_hi:[1,0]
	v_max_f32_e32 v124, 0, v124
	v_max_f32_e32 v125, 0, v125
	v_max_f32_e32 v104, 0, v104
	v_cndmask_b32_e64 v162, v155, v167, s[0:1]
	v_pk_mul_f32 v[110:111], v[110:111], v[158:159] op_sel_hi:[1,0]
	v_max_f32_e32 v120, 0, v120
	v_max_f32_e32 v121, 0, v121
	v_max_f32_e32 v126, 0, v126
	v_max_f32_e32 v122, 0, v122
	v_max_f32_e32 v127, 0, v127
	v_max_f32_e32 v123, 0, v123
	v_max_f32_e32 v108, 0, v108
	v_max_f32_e32 v109, 0, v109
	v_max_f32_e32 v105, 0, v105
	v_max_f32_e32 v106, 0, v106
	v_max_f32_e32 v107, 0, v107
	v_mul_f32_e32 v124, v124, v124
	v_mul_f32_e32 v125, v125, v125
	v_mul_f32_e32 v155, v104, v104
	v_cvt_pk_bf16_f32 v104, v124, v125
	v_fmamk_f32 v147, v168, 0x3a800000, v154
	v_pk_mul_f32 v[112:113], v[112:113], v[162:163] op_sel_hi:[1,0]
	v_max_f32_e32 v110, 0, v110
	v_max_f32_e32 v111, 0, v111
	v_mul_f32_e32 v120, v120, v120
	v_mul_f32_e32 v121, v121, v121
	v_mul_f32_e32 v126, v126, v126
	v_mul_f32_e32 v122, v122, v122
	v_mul_f32_e32 v127, v127, v127
	v_mul_f32_e32 v123, v123, v123
	v_mul_f32_e32 v108, v108, v108
	v_mul_f32_e32 v109, v109, v109
	v_mul_f32_e32 v158, v105, v105
	v_mul_f32_e32 v167, v106, v106
	v_mul_f32_e32 v168, v107, v107
	v_cvt_pk_bf16_f32 v105, v126, v127
	v_cvt_pk_bf16_f32 v106, v120, v121
	v_cvt_pk_bf16_f32 v107, v122, v123
	global_store_dwordx4 v[144:145], v[104:107], off nt
	v_pk_mul_f32 v[116:117], v[116:117], v[162:163] op_sel_hi:[1,0]
	v_mul_f32_e32 v110, v110, v110
	v_cvt_pk_bf16_f32 v104, v108, v109
	v_mul_f32_e32 v111, v111, v111
	v_cvt_pk_bf16_f32 v105, v110, v111
	v_cvt_pk_bf16_f32 v106, v155, v158
	v_cvt_pk_bf16_f32 v107, v167, v168
	global_store_dwordx4 v[144:145], v[104:107], off offset:256 nt
	v_pk_mul_f32 v[118:119], v[118:119], v[162:163] op_sel_hi:[1,0]
	v_pk_mul_f32 v[114:115], v[114:115], v[162:163] op_sel_hi:[1,0]
	v_max_f32_e32 v104, 0, v112
	v_mul_f32_e32 v106, v104, v104
	v_max_f32_e32 v104, 0, v117
	v_max_f32_e32 v116, 0, v116
	v_max_f32_e32 v107, 0, v113
	v_mul_f32_e32 v104, v104, v104
	v_pk_mul_f32 v[98:99], v[98:99], v[162:163] op_sel_hi:[1,0]
	v_pk_mul_f32 v[96:97], v[96:97], v[162:163] op_sel_hi:[1,0]
	v_mul_f32_e32 v105, v116, v116
	v_mul_f32_e32 v107, v107, v107
	v_max_f32_e32 v108, 0, v118
	v_max_f32_e32 v109, 0, v114
	v_max_f32_e32 v110, 0, v119
	v_max_f32_e32 v111, 0, v115
	v_cvt_pk_bf16_f32 v104, v105, v104
	v_pk_mul_f32 v[102:103], v[102:103], v[162:163] op_sel_hi:[1,0]
	v_pk_mul_f32 v[100:101], v[100:101], v[162:163] op_sel_hi:[1,0]
	v_max_f32_e32 v96, 0, v96
	v_max_f32_e32 v97, 0, v97
	v_max_f32_e32 v98, 0, v98
	v_mul_f32_e32 v108, v108, v108
	v_mul_f32_e32 v109, v109, v109
	v_mul_f32_e32 v110, v110, v110
	v_mul_f32_e32 v111, v111, v111
	v_cvt_pk_bf16_f32 v105, v108, v110
	v_cvt_pk_bf16_f32 v106, v106, v107
	v_cvt_pk_bf16_f32 v107, v109, v111
	global_store_dwordx4 v[156:157], v[104:107], off nt
	v_max_f32_e32 v100, 0, v100
	v_max_f32_e32 v99, 0, v99
	v_mul_f32_e32 v104, v96, v96
	v_max_f32_e32 v96, 0, v101
	v_mul_f32_e32 v101, v97, v97
	v_max_f32_e32 v97, 0, v102
	v_mul_f32_e32 v102, v98, v98
	v_max_f32_e32 v98, 0, v103
	v_mul_f32_e32 v96, v96, v96
	v_mul_f32_e32 v97, v97, v97
	v_mul_f32_e32 v98, v98, v98
	v_mul_f32_e32 v100, v100, v100
	v_mul_f32_e32 v99, v99, v99
	v_cvt_pk_bf16_f32 v96, v100, v96
	v_cvt_pk_bf16_f32 v97, v97, v98
	v_cvt_pk_bf16_f32 v98, v104, v101
	v_cvt_pk_bf16_f32 v99, v102, v99
	global_store_dwordx4 v[156:157], v[96:99], off offset:256 nt
	v_cmp_gt_f32_e32 vcc, s54, v159
	s_mov_b32 s1, s20
	v_mul_f32_e32 v98, 0x4b800000, v159
	v_cndmask_b32_e32 v98, v159, v98, vcc
	v_rsq_f32_e32 v98, v98
	v_or_b32_e32 v96, 32, v146
	v_ashrrev_i32_e32 v97, 31, v96
	v_lshlrev_b64 v[96:97], 13, v[96:97]
	v_mul_f32_e32 v99, 0x45800000, v98
	v_cndmask_b32_e32 v98, v98, v99, vcc
	v_pk_mul_f32 v[88:89], v[88:89], v[98:99] op_sel_hi:[1,0]
	v_pk_mul_f32 v[92:93], v[92:93], v[98:99] op_sel_hi:[1,0]
	v_pk_mul_f32 v[90:91], v[90:91], v[98:99] op_sel_hi:[1,0]
	v_max_f32_e32 v88, 0, v88
	v_pk_mul_f32 v[94:95], v[94:95], v[98:99] op_sel_hi:[1,0]
	v_mul_f32_e32 v99, v88, v88
	v_max_f32_e32 v88, 0, v93
	v_max_f32_e32 v89, 0, v89
	v_max_f32_e32 v90, 0, v90
	v_lshl_add_u64 v[96:97], s[92:93], 0, v[96:97]
	v_max_f32_e32 v92, 0, v92
	v_mul_f32_e32 v88, v88, v88
	v_mul_f32_e32 v93, v89, v89
	v_max_f32_e32 v89, 0, v94
	v_mul_f32_e32 v94, v90, v90
	v_max_f32_e32 v90, 0, v95
	v_max_f32_e32 v91, 0, v91
	v_pk_mul_f32 v[82:83], v[82:83], v[98:99] op_sel_hi:[1,0]
	v_pk_mul_f32 v[80:81], v[80:81], v[98:99] op_sel_hi:[1,0]
	v_lshl_add_u64 v[96:97], v[96:97], 0, v[160:161]
	v_mul_f32_e32 v92, v92, v92
	v_mul_f32_e32 v89, v89, v89
	v_mul_f32_e32 v90, v90, v90
	v_mul_f32_e32 v91, v91, v91
	v_cvt_pk_bf16_f32 v88, v92, v88
	v_pk_mul_f32 v[86:87], v[86:87], v[98:99] op_sel_hi:[1,0]
	v_pk_mul_f32 v[84:85], v[84:85], v[98:99] op_sel_hi:[1,0]
	v_max_f32_e32 v80, 0, v80
	v_max_f32_e32 v81, 0, v81
	v_max_f32_e32 v82, 0, v82
	v_cvt_pk_bf16_f32 v89, v89, v90
	v_cvt_pk_bf16_f32 v90, v99, v93
	v_cvt_pk_bf16_f32 v91, v94, v91
	global_store_dwordx4 v[96:97], v[88:91], off nt
	v_max_f32_e32 v84, 0, v84
	v_max_f32_e32 v83, 0, v83
	v_mul_f32_e32 v88, v80, v80
	v_max_f32_e32 v80, 0, v85
	v_mul_f32_e32 v85, v81, v81
	v_max_f32_e32 v81, 0, v86
	v_mul_f32_e32 v86, v82, v82
	v_max_f32_e32 v82, 0, v87
	v_mul_f32_e32 v80, v80, v80
	v_mul_f32_e32 v81, v81, v81
	v_mul_f32_e32 v82, v82, v82
	v_mul_f32_e32 v84, v84, v84
	v_mul_f32_e32 v83, v83, v83
	v_cvt_pk_bf16_f32 v80, v84, v80
	v_cvt_pk_bf16_f32 v81, v81, v82
	v_cvt_pk_bf16_f32 v82, v88, v85
	v_cvt_pk_bf16_f32 v83, v86, v83
	global_store_dwordx4 v[96:97], v[80:83], off offset:256 nt
	v_cmp_gt_f32_e32 vcc, s54, v163
	s_mov_b32 s0, s22
	v_mul_f32_e32 v82, 0x4b800000, v163
	v_cndmask_b32_e32 v82, v163, v82, vcc
	v_rsq_f32_e32 v82, v82
	v_or_b32_e32 v80, 48, v146
	v_ashrrev_i32_e32 v81, 31, v80
	v_lshlrev_b64 v[80:81], 13, v[80:81]
	v_mul_f32_e32 v83, 0x45800000, v82
	v_cndmask_b32_e32 v82, v82, v83, vcc
	v_pk_mul_f32 v[72:73], v[72:73], v[82:83] op_sel_hi:[1,0]
	v_pk_mul_f32 v[76:77], v[76:77], v[82:83] op_sel_hi:[1,0]
	v_pk_mul_f32 v[74:75], v[74:75], v[82:83] op_sel_hi:[1,0]
	v_max_f32_e32 v72, 0, v72
	v_pk_mul_f32 v[78:79], v[78:79], v[82:83] op_sel_hi:[1,0]
	v_mul_f32_e32 v83, v72, v72
	v_max_f32_e32 v72, 0, v77
	v_max_f32_e32 v73, 0, v73
	v_max_f32_e32 v74, 0, v74
	v_lshl_add_u64 v[80:81], s[92:93], 0, v[80:81]
	v_max_f32_e32 v76, 0, v76
	v_mul_f32_e32 v72, v72, v72
	v_mul_f32_e32 v77, v73, v73
	v_max_f32_e32 v73, 0, v78
	v_mul_f32_e32 v78, v74, v74
	v_max_f32_e32 v74, 0, v79
	v_max_f32_e32 v75, 0, v75
	v_pk_mul_f32 v[64:65], v[64:65], v[82:83] op_sel_hi:[1,0]
	v_lshl_add_u64 v[80:81], v[80:81], 0, v[160:161]
	v_mul_f32_e32 v76, v76, v76
	v_mul_f32_e32 v73, v73, v73
	v_mul_f32_e32 v74, v74, v74
	v_mul_f32_e32 v75, v75, v75
	v_cvt_pk_bf16_f32 v72, v76, v72
	v_pk_mul_f32 v[68:69], v[68:69], v[82:83] op_sel_hi:[1,0]
	v_max_f32_e32 v64, 0, v64
	v_cvt_pk_bf16_f32 v73, v73, v74
	v_cvt_pk_bf16_f32 v74, v83, v77
	v_cvt_pk_bf16_f32 v75, v78, v75
	global_store_dwordx4 v[80:81], v[72:75], off nt
	v_max_f32_e32 v68, 0, v68
	v_mul_f32_e32 v68, v68, v68
	v_mul_f32_e32 v72, v64, v64
	v_max_f32_e32 v64, 0, v69
	v_mul_f32_e32 v64, v64, v64
	v_cvt_pk_bf16_f32 v64, v68, v64
	v_mul_f32_e32 v68, 0x4b800000, v164
	v_cmp_gt_f32_e32 vcc, s54, v164
	v_pk_mul_f32 v[66:67], v[66:67], v[82:83] op_sel_hi:[1,0]
	v_pk_mul_f32 v[70:71], v[70:71], v[82:83] op_sel_hi:[1,0]
	v_cndmask_b32_e32 v68, v164, v68, vcc
	v_max_f32_e32 v65, 0, v65
	v_max_f32_e32 v66, 0, v66
	v_rsq_f32_e32 v68, v68
	v_mul_f32_e32 v69, v65, v65
	v_max_f32_e32 v65, 0, v70
	v_mul_f32_e32 v70, v66, v66
	v_max_f32_e32 v66, 0, v71
	v_mul_f32_e32 v65, v65, v65
	v_max_f32_e32 v67, 0, v67
	v_mul_f32_e32 v66, v66, v66
	v_mul_f32_e32 v67, v67, v67
	v_cvt_pk_bf16_f32 v65, v65, v66
	v_cvt_pk_bf16_f32 v66, v72, v69
	v_cvt_pk_bf16_f32 v67, v70, v67
	global_store_dwordx4 v[80:81], v[64:67], off offset:256 nt
	s_nop 1
	v_mul_f32_e32 v66, 0x45800000, v68
	v_cndmask_b32_e32 v66, v68, v66, vcc
	v_pk_mul_f32 v[56:57], v[56:57], v[66:67] op_sel_hi:[1,0]
	v_pk_mul_f32 v[60:61], v[60:61], v[66:67] op_sel_hi:[1,0]
	v_pk_mul_f32 v[58:59], v[58:59], v[66:67] op_sel_hi:[1,0]
	v_max_f32_e32 v56, 0, v56
	v_pk_mul_f32 v[62:63], v[62:63], v[66:67] op_sel_hi:[1,0]
	v_max_f32_e32 v60, 0, v60
	v_mul_f32_e32 v67, v56, v56
	v_max_f32_e32 v56, 0, v61
	v_max_f32_e32 v57, 0, v57
	v_max_f32_e32 v58, 0, v58
	v_mul_f32_e32 v60, v60, v60
	v_mul_f32_e32 v56, v56, v56
	v_mul_f32_e32 v61, v57, v57
	v_max_f32_e32 v57, 0, v62
	v_mul_f32_e32 v62, v58, v58
	v_max_f32_e32 v58, 0, v63
	v_mul_f32_e32 v57, v57, v57
	v_max_f32_e32 v59, 0, v59
	v_mul_f32_e32 v58, v58, v58
	v_cvt_pk_bf16_f32 v56, v60, v56
	v_add_co_u32_e32 v60, vcc, s55, v144
	v_pk_mul_f32 v[48:49], v[48:49], v[66:67] op_sel_hi:[1,0]
	v_mul_f32_e32 v59, v59, v59
	v_cvt_pk_bf16_f32 v57, v57, v58
	v_cvt_pk_bf16_f32 v58, v67, v61
	v_addc_co_u32_e32 v61, vcc, 0, v145, vcc
	v_pk_mul_f32 v[52:53], v[52:53], v[66:67] op_sel_hi:[1,0]
	v_max_f32_e32 v48, 0, v48
	v_cvt_pk_bf16_f32 v59, v62, v59
	global_store_dwordx4 v[60:61], v[56:59], off nt
	v_max_f32_e32 v52, 0, v52
	v_mul_f32_e32 v52, v52, v52
	v_mul_f32_e32 v56, v48, v48
	v_max_f32_e32 v48, 0, v53
	v_mul_f32_e32 v48, v48, v48
	v_cvt_pk_bf16_f32 v48, v52, v48
	v_mul_f32_e32 v52, 0x4b800000, v165
	v_cmp_gt_f32_e32 vcc, s54, v165
	v_pk_mul_f32 v[50:51], v[50:51], v[66:67] op_sel_hi:[1,0]
	v_pk_mul_f32 v[54:55], v[54:55], v[66:67] op_sel_hi:[1,0]
	v_cndmask_b32_e32 v52, v165, v52, vcc
	v_max_f32_e32 v49, 0, v49
	v_max_f32_e32 v50, 0, v50
	v_rsq_f32_e32 v52, v52
	v_mul_f32_e32 v53, v49, v49
	v_max_f32_e32 v49, 0, v54
	v_mul_f32_e32 v54, v50, v50
	v_max_f32_e32 v50, 0, v55
	v_mul_f32_e32 v49, v49, v49
	v_max_f32_e32 v51, 0, v51
	v_mul_f32_e32 v50, v50, v50
	v_lshl_add_u64 v[64:65], v[144:145], 0, s[12:13]
	v_mul_f32_e32 v51, v51, v51
	v_cvt_pk_bf16_f32 v49, v49, v50
	v_cvt_pk_bf16_f32 v50, v56, v53
	v_cvt_pk_bf16_f32 v51, v54, v51
	global_store_dwordx4 v[64:65], v[48:51], off offset:256 nt
	s_nop 1
	v_mul_f32_e32 v50, 0x45800000, v52
	v_cndmask_b32_e32 v50, v52, v50, vcc
	v_pk_mul_f32 v[40:41], v[40:41], v[50:51] op_sel_hi:[1,0]
	v_pk_mul_f32 v[44:45], v[44:45], v[50:51] op_sel_hi:[1,0]
	v_pk_mul_f32 v[42:43], v[42:43], v[50:51] op_sel_hi:[1,0]
	v_max_f32_e32 v40, 0, v40
	v_pk_mul_f32 v[46:47], v[46:47], v[50:51] op_sel_hi:[1,0]
	v_max_f32_e32 v44, 0, v44
	v_mul_f32_e32 v51, v40, v40
	v_max_f32_e32 v40, 0, v45
	v_max_f32_e32 v41, 0, v41
	v_max_f32_e32 v42, 0, v42
	v_mul_f32_e32 v44, v44, v44
	v_mul_f32_e32 v40, v40, v40
	v_mul_f32_e32 v45, v41, v41
	v_max_f32_e32 v41, 0, v46
	v_mul_f32_e32 v46, v42, v42
	v_max_f32_e32 v42, 0, v47
	v_mul_f32_e32 v41, v41, v41
	v_max_f32_e32 v43, 0, v43
	v_mul_f32_e32 v42, v42, v42
	v_cvt_pk_bf16_f32 v40, v44, v40
	v_add_co_u32_e32 v44, vcc, s56, v144
	v_pk_mul_f32 v[32:33], v[32:33], v[50:51] op_sel_hi:[1,0]
	v_mul_f32_e32 v43, v43, v43
	v_cvt_pk_bf16_f32 v41, v41, v42
	v_cvt_pk_bf16_f32 v42, v51, v45
	v_addc_co_u32_e32 v45, vcc, 0, v145, vcc
	v_pk_mul_f32 v[36:37], v[36:37], v[50:51] op_sel_hi:[1,0]
	v_max_f32_e32 v32, 0, v32
	v_cvt_pk_bf16_f32 v43, v46, v43
	global_store_dwordx4 v[44:45], v[40:43], off nt
	v_max_f32_e32 v36, 0, v36
	v_mul_f32_e32 v36, v36, v36
	v_mul_f32_e32 v40, v32, v32
	v_max_f32_e32 v32, 0, v37
	v_mul_f32_e32 v32, v32, v32
	v_cvt_pk_bf16_f32 v32, v36, v32
	v_mul_f32_e32 v36, 0x4b800000, v166
	v_cmp_gt_f32_e32 vcc, s54, v166
	v_pk_mul_f32 v[34:35], v[34:35], v[50:51] op_sel_hi:[1,0]
	v_pk_mul_f32 v[38:39], v[38:39], v[50:51] op_sel_hi:[1,0]
	v_cndmask_b32_e32 v36, v166, v36, vcc
	v_max_f32_e32 v33, 0, v33
	v_max_f32_e32 v34, 0, v34
	v_rsq_f32_e32 v36, v36
	v_mul_f32_e32 v37, v33, v33
	v_max_f32_e32 v33, 0, v38
	v_mul_f32_e32 v38, v34, v34
	v_max_f32_e32 v34, 0, v39
	v_mul_f32_e32 v33, v33, v33
	v_max_f32_e32 v35, 0, v35
	v_mul_f32_e32 v34, v34, v34
	v_lshl_add_u64 v[48:49], v[144:145], 0, s[14:15]
	v_mul_f32_e32 v35, v35, v35
	v_cvt_pk_bf16_f32 v33, v33, v34
	v_cvt_pk_bf16_f32 v34, v40, v37
	v_cvt_pk_bf16_f32 v35, v38, v35
	global_store_dwordx4 v[48:49], v[32:35], off offset:256 nt
	s_nop 1
	v_mul_f32_e32 v34, 0x45800000, v36
	v_cndmask_b32_e32 v34, v36, v34, vcc
	v_pk_mul_f32 v[24:25], v[24:25], v[34:35] op_sel_hi:[1,0]
	v_pk_mul_f32 v[28:29], v[28:29], v[34:35] op_sel_hi:[1,0]
	v_pk_mul_f32 v[26:27], v[26:27], v[34:35] op_sel_hi:[1,0]
	v_max_f32_e32 v24, 0, v24
	v_pk_mul_f32 v[30:31], v[30:31], v[34:35] op_sel_hi:[1,0]
	v_max_f32_e32 v28, 0, v28
	v_mul_f32_e32 v35, v24, v24
	v_max_f32_e32 v24, 0, v29
	v_max_f32_e32 v25, 0, v25
	v_max_f32_e32 v26, 0, v26
	v_mul_f32_e32 v28, v28, v28
	v_mul_f32_e32 v24, v24, v24
	v_mul_f32_e32 v29, v25, v25
	v_max_f32_e32 v25, 0, v30
	v_mul_f32_e32 v30, v26, v26
	v_max_f32_e32 v26, 0, v31
	v_mul_f32_e32 v25, v25, v25
	v_max_f32_e32 v27, 0, v27
	v_mul_f32_e32 v26, v26, v26
	v_cvt_pk_bf16_f32 v24, v28, v24
	v_add_co_u32_e32 v28, vcc, s57, v144
	v_pk_mul_f32 v[16:17], v[16:17], v[34:35] op_sel_hi:[1,0]
	v_mul_f32_e32 v27, v27, v27
	v_cvt_pk_bf16_f32 v25, v25, v26
	v_cvt_pk_bf16_f32 v26, v35, v29
	v_addc_co_u32_e32 v29, vcc, 0, v145, vcc
	v_pk_mul_f32 v[20:21], v[20:21], v[34:35] op_sel_hi:[1,0]
	v_max_f32_e32 v16, 0, v16
	v_cvt_pk_bf16_f32 v27, v30, v27
	global_store_dwordx4 v[28:29], v[24:27], off nt
	v_max_f32_e32 v20, 0, v20
	v_mul_f32_e32 v20, v20, v20
	v_mul_f32_e32 v24, v16, v16
	v_max_f32_e32 v16, 0, v21
	v_mul_f32_e32 v16, v16, v16
	v_cvt_pk_bf16_f32 v16, v20, v16
	v_mul_f32_e32 v20, 0x4b800000, v147
	v_cmp_gt_f32_e32 vcc, s54, v147
	v_pk_mul_f32 v[18:19], v[18:19], v[34:35] op_sel_hi:[1,0]
	v_pk_mul_f32 v[22:23], v[22:23], v[34:35] op_sel_hi:[1,0]
	v_cndmask_b32_e32 v20, v147, v20, vcc
	v_max_f32_e32 v17, 0, v17
	v_max_f32_e32 v18, 0, v18
	v_rsq_f32_e32 v20, v20
	v_mul_f32_e32 v21, v17, v17
	v_max_f32_e32 v17, 0, v22
	v_mul_f32_e32 v22, v18, v18
	v_max_f32_e32 v18, 0, v23
	v_mul_f32_e32 v17, v17, v17
	v_max_f32_e32 v19, 0, v19
	v_mul_f32_e32 v18, v18, v18
	v_lshl_add_u64 v[32:33], v[144:145], 0, s[16:17]
	v_mul_f32_e32 v19, v19, v19
	v_cvt_pk_bf16_f32 v17, v17, v18
	v_cvt_pk_bf16_f32 v18, v24, v21
	v_cvt_pk_bf16_f32 v19, v22, v19
	global_store_dwordx4 v[32:33], v[16:19], off offset:256 nt
	s_nop 1
	v_mul_f32_e32 v18, 0x45800000, v20
	v_cndmask_b32_e32 v18, v20, v18, vcc
	v_pk_mul_f32 v[8:9], v[8:9], v[18:19] op_sel_hi:[1,0]
	v_pk_mul_f32 v[12:13], v[12:13], v[18:19] op_sel_hi:[1,0]
	v_pk_mul_f32 v[10:11], v[10:11], v[18:19] op_sel_hi:[1,0]
	v_max_f32_e32 v8, 0, v8
	v_pk_mul_f32 v[14:15], v[14:15], v[18:19] op_sel_hi:[1,0]
	v_max_f32_e32 v12, 0, v12
	v_mul_f32_e32 v19, v8, v8
	v_max_f32_e32 v8, 0, v13
	v_max_f32_e32 v9, 0, v9
	v_max_f32_e32 v10, 0, v10
	v_mul_f32_e32 v12, v12, v12
	v_mul_f32_e32 v8, v8, v8
	v_mul_f32_e32 v13, v9, v9
	v_max_f32_e32 v9, 0, v14
	v_mul_f32_e32 v14, v10, v10
	v_max_f32_e32 v10, 0, v15
	v_mul_f32_e32 v9, v9, v9
	v_max_f32_e32 v11, 0, v11
	v_mul_f32_e32 v10, v10, v10
	v_cvt_pk_bf16_f32 v8, v12, v8
	v_add_co_u32_e32 v12, vcc, s58, v144
	v_pk_mul_f32 v[2:3], v[2:3], v[18:19] op_sel_hi:[1,0]
	v_pk_mul_f32 v[0:1], v[0:1], v[18:19] op_sel_hi:[1,0]
	v_mul_f32_e32 v11, v11, v11
	v_cvt_pk_bf16_f32 v9, v9, v10
	v_cvt_pk_bf16_f32 v10, v19, v13
	v_addc_co_u32_e32 v13, vcc, 0, v145, vcc
	v_pk_mul_f32 v[6:7], v[6:7], v[18:19] op_sel_hi:[1,0]
	v_pk_mul_f32 v[4:5], v[4:5], v[18:19] op_sel_hi:[1,0]
	v_max_f32_e32 v0, 0, v0
	v_max_f32_e32 v1, 0, v1
	v_max_f32_e32 v2, 0, v2
	v_cvt_pk_bf16_f32 v11, v14, v11
	global_store_dwordx4 v[12:13], v[8:11], off nt
	v_max_f32_e32 v3, 0, v3
	v_lshl_add_u64 v[16:17], v[144:145], 0, s[18:19]
	v_mul_f32_e32 v8, v0, v0
	v_max_f32_e32 v0, 0, v5
	v_mul_f32_e32 v5, v1, v1
	v_max_f32_e32 v1, 0, v6
	v_mul_f32_e32 v6, v2, v2
	v_max_f32_e32 v2, 0, v7
	v_max_f32_e32 v4, 0, v4
	v_mul_f32_e32 v0, v0, v0
	v_mul_f32_e32 v1, v1, v1
	v_mul_f32_e32 v2, v2, v2
	v_mul_f32_e32 v3, v3, v3
	s_and_b64 vcc, exec, s[2:3]
	v_mul_f32_e32 v4, v4, v4
	v_cvt_pk_bf16_f32 v0, v4, v0
	v_cvt_pk_bf16_f32 v1, v1, v2
	v_cvt_pk_bf16_f32 v2, v8, v5
	v_cvt_pk_bf16_f32 v3, v6, v3
	global_store_dwordx4 v[16:17], v[0:3], off offset:256 nt
	s_cbranch_vccz .LBB0_1211
	s_waitcnt vmcnt(0)
	s_cmpk_gt_u32 s33, 0xff
	s_cbranch_scc1 .LBB0_1222
	s_barrier
